# leading half runs epilogue + next-tile startup at prio 1 (staggers the two halves' epilogues so the leader's first load segment overlaps the trailer's epilogue tail)
# baseline (speedup 1.0000x reference)
.Lph217_w:
	s_nop 0
	s_nop 0
	s_waitcnt vmcnt(8)
	s_waitcnt lgkmcnt(0)
	s_setprio 1
	s_barrier
	v_mfma_f32_16x16x32_bf16 v[124:127], v[146:149], v[186:189], v[124:127]
	v_mfma_f32_16x16x32_bf16 v[120:123], v[162:165], v[186:189], v[120:123]
	v_mfma_f32_16x16x32_bf16 v[108:111], v[146:149], v[194:197], v[108:111]
	v_mfma_f32_16x16x32_bf16 v[104:107], v[162:165], v[194:197], v[104:107]
	v_mfma_f32_16x16x32_bf16 v[92:95], v[146:149], v[202:205], v[92:95]
	v_mfma_f32_16x16x32_bf16 v[88:91], v[162:165], v[202:205], v[88:91]
	v_mfma_f32_16x16x32_bf16 v[76:79], v[146:149], v[210:213], v[76:79]
	v_mfma_f32_16x16x32_bf16 v[72:75], v[162:165], v[210:213], v[72:75]
	v_mfma_f32_16x16x32_bf16 v[124:127], v[158:161], v[190:193], v[124:127]
	v_mfma_f32_16x16x32_bf16 v[120:123], v[166:169], v[190:193], v[120:123]
	v_mfma_f32_16x16x32_bf16 v[108:111], v[158:161], v[198:201], v[108:111]
	v_mfma_f32_16x16x32_bf16 v[104:107], v[166:169], v[198:201], v[104:107]
	v_mfma_f32_16x16x32_bf16 v[92:95], v[158:161], v[206:209], v[92:95]
	v_mfma_f32_16x16x32_bf16 v[88:91], v[166:169], v[206:209], v[88:91]
	v_mfma_f32_16x16x32_bf16 v[76:79], v[158:161], v[214:217], v[76:79]
	v_mfma_f32_16x16x32_bf16 v[72:75], v[166:169], v[214:217], v[72:75]
	s_setprio 0
	s_setprio 1
	v_mfma_f32_16x16x32_bf16 v[116:119], v[170:173], v[186:189], v[116:119]
	v_mfma_f32_16x16x32_bf16 v[112:115], v[178:181], v[186:189], v[112:115]
	v_mfma_f32_16x16x32_bf16 v[100:103], v[170:173], v[194:197], v[100:103]
	v_mfma_f32_16x16x32_bf16 v[96:99], v[178:181], v[194:197], v[96:99]
	v_mfma_f32_16x16x32_bf16 v[84:87], v[170:173], v[202:205], v[84:87]
	v_mfma_f32_16x16x32_bf16 v[80:83], v[178:181], v[202:205], v[80:83]
	v_mfma_f32_16x16x32_bf16 v[68:71], v[170:173], v[210:213], v[68:71]
	v_mfma_f32_16x16x32_bf16 v[64:67], v[178:181], v[210:213], v[64:67]
	v_mfma_f32_16x16x32_bf16 v[116:119], v[174:177], v[190:193], v[116:119]
	v_mfma_f32_16x16x32_bf16 v[112:115], v[182:185], v[190:193], v[112:115]
	v_mfma_f32_16x16x32_bf16 v[100:103], v[174:177], v[198:201], v[100:103]
	v_mfma_f32_16x16x32_bf16 v[96:99], v[182:185], v[198:201], v[96:99]
	v_mfma_f32_16x16x32_bf16 v[84:87], v[174:177], v[206:209], v[84:87]
	v_mfma_f32_16x16x32_bf16 v[80:83], v[182:185], v[206:209], v[80:83]
	v_mfma_f32_16x16x32_bf16 v[68:71], v[174:177], v[214:217], v[68:71]
	v_mfma_f32_16x16x32_bf16 v[64:67], v[182:185], v[214:217], v[64:67]
	s_barrier
	s_setprio 0
	s_add_i32 s72, s65, s43
	v_lshl_add_u64 v[150:151], s[36:37], 0, v[130:131]
	s_mov_b32 m0, s72
	s_nop 0
	global_load_lds_dwordx4 v[150:151], off
	s_add_i32 m0, s72, 0x2000
	s_add_u32 s72, s36, 0x40000
	v_lshl_add_u64 v[218:219], s[36:37], 0, v[134:135]
	s_addc_u32 s73, s37, 0
	s_add_i32 s74, s67, s43
	global_load_lds_dwordx4 v[218:219], off
	v_lshl_add_u64 v[220:221], s[72:73], 0, v[130:131]
	s_mov_b32 m0, s74
	v_lshl_add_u64 v[222:223], s[38:39], 0, v[132:133]
	global_load_lds_dwordx4 v[220:221], off
	v_lshl_add_u64 v[220:221], s[72:73], 0, v[134:135]
	s_add_i32 m0, s74, 0x2000
	s_nop 0
	global_load_lds_dwordx4 v[220:221], off
	v_lshl_add_u64 v[220:221], s[38:39], 0, v[128:129]
	s_mov_b32 m0, s31
	s_nop 0
	global_load_lds_dwordx4 v[220:221], off
	s_mov_b32 m0, s46
	s_nop 0
	global_load_lds_dwordx4 v[222:223], off
	ds_read_b128 v[186:189], v157 offset:16384
	ds_read_b128 v[190:193], v157 offset:17408
	ds_read_b128 v[194:197], v157 offset:18432
	ds_read_b128 v[198:201], v157 offset:19456
	ds_read_b128 v[202:205], v157 offset:20480
	ds_read_b128 v[206:209], v157 offset:21504
	ds_read_b128 v[210:213], v157 offset:22528
	ds_read_b128 v[214:217], v157 offset:23552
	s_nop 0
	s_waitcnt vmcnt(8)
	s_waitcnt lgkmcnt(0)
	s_setprio 1
	s_barrier
	v_mfma_f32_16x16x32_bf16 v[60:63], v[146:149], v[186:189], v[60:63]
	v_mfma_f32_16x16x32_bf16 v[56:59], v[162:165], v[186:189], v[56:59]
	v_mfma_f32_16x16x32_bf16 v[44:47], v[146:149], v[194:197], v[44:47]
	v_mfma_f32_16x16x32_bf16 v[40:43], v[162:165], v[194:197], v[40:43]
	v_mfma_f32_16x16x32_bf16 v[28:31], v[146:149], v[202:205], v[28:31]
	v_mfma_f32_16x16x32_bf16 v[24:27], v[162:165], v[202:205], v[24:27]
	v_mfma_f32_16x16x32_bf16 v[12:15], v[146:149], v[210:213], v[12:15]
	v_mfma_f32_16x16x32_bf16 v[8:11], v[162:165], v[210:213], v[8:11]
	v_mfma_f32_16x16x32_bf16 v[60:63], v[158:161], v[190:193], v[60:63]
	v_mfma_f32_16x16x32_bf16 v[56:59], v[166:169], v[190:193], v[56:59]
	v_mfma_f32_16x16x32_bf16 v[44:47], v[158:161], v[198:201], v[44:47]
	v_mfma_f32_16x16x32_bf16 v[40:43], v[166:169], v[198:201], v[40:43]
	v_mfma_f32_16x16x32_bf16 v[28:31], v[158:161], v[206:209], v[28:31]
	v_mfma_f32_16x16x32_bf16 v[24:27], v[166:169], v[206:209], v[24:27]
	v_mfma_f32_16x16x32_bf16 v[12:15], v[158:161], v[214:217], v[12:15]
	v_mfma_f32_16x16x32_bf16 v[8:11], v[166:169], v[214:217], v[8:11]
	s_setprio 0
	s_setprio 1
	v_mfma_f32_16x16x32_bf16 v[52:55], v[170:173], v[186:189], v[52:55]
	v_mfma_f32_16x16x32_bf16 v[48:51], v[178:181], v[186:189], v[48:51]
	v_mfma_f32_16x16x32_bf16 v[36:39], v[170:173], v[194:197], v[36:39]
	v_mfma_f32_16x16x32_bf16 v[32:35], v[178:181], v[194:197], v[32:35]
	v_mfma_f32_16x16x32_bf16 v[20:23], v[170:173], v[202:205], v[20:23]
	v_mfma_f32_16x16x32_bf16 v[16:19], v[178:181], v[202:205], v[16:19]
	v_mfma_f32_16x16x32_bf16 v[4:7], v[170:173], v[210:213], v[4:7]
	v_mfma_f32_16x16x32_bf16 v[0:3], v[178:181], v[210:213], v[0:3]
	v_mfma_f32_16x16x32_bf16 v[52:55], v[174:177], v[190:193], v[52:55]
	v_mfma_f32_16x16x32_bf16 v[48:51], v[182:185], v[190:193], v[48:51]
	v_mfma_f32_16x16x32_bf16 v[36:39], v[174:177], v[198:201], v[36:39]
	v_mfma_f32_16x16x32_bf16 v[32:35], v[182:185], v[198:201], v[32:35]
	v_mfma_f32_16x16x32_bf16 v[20:23], v[174:177], v[206:209], v[20:23]
	v_mfma_f32_16x16x32_bf16 v[16:19], v[182:185], v[206:209], v[16:19]
	v_mfma_f32_16x16x32_bf16 v[4:7], v[174:177], v[214:217], v[4:7]
	v_mfma_f32_16x16x32_bf16 v[0:3], v[182:185], v[214:217], v[0:3]
	s_barrier
	s_setprio 0
	s_add_i32 s72, 0, 0x18000
	s_add_i32 s73, 0, 0x1c000
	s_add_u32 s38, s38, 0x40000
	s_addc_u32 s39, s39, 0
	s_mov_b32 m0, s47
	v_lshl_add_u64 v[224:225], s[38:39], 0, v[128:129]
	global_load_lds_dwordx4 v[224:225], off
	v_lshl_add_u64 v[224:225], s[38:39], 0, v[132:133]
	s_mov_b32 m0, s48
	s_nop 0
	global_load_lds_dwordx4 v[224:225], off
	v_add_u32_e32 v136, s72, v153
	ds_read_b128 v[146:149], v136
	ds_read_b128 v[158:161], v136 offset:1024
	ds_read_b128 v[162:165], v136 offset:2048
	ds_read_b128 v[166:169], v136 offset:3072
	v_add_u32_e32 v136, s73, v153
	ds_read_b128 v[170:173], v136
	ds_read_b128 v[174:177], v136 offset:1024
	ds_read_b128 v[178:181], v136 offset:2048
	ds_read_b128 v[182:185], v136 offset:3072
	ds_read_b128 v[186:189], v157 offset:32768
	ds_read_b128 v[190:193], v157 offset:33792
	ds_read_b128 v[194:197], v157 offset:34816
	ds_read_b128 v[198:201], v157 offset:35840
	ds_read_b128 v[202:205], v157 offset:36864
	ds_read_b128 v[206:209], v157 offset:37888
	ds_read_b128 v[210:213], v157 offset:38912
	ds_read_b128 v[214:217], v157 offset:39936
	s_waitcnt vmcnt(8)
	s_waitcnt lgkmcnt(0)
	s_setprio 1
	s_barrier
	v_mfma_f32_16x16x32_bf16 v[124:127], v[146:149], v[186:189], v[124:127]
	v_mfma_f32_16x16x32_bf16 v[120:123], v[162:165], v[186:189], v[120:123]
	v_mfma_f32_16x16x32_bf16 v[108:111], v[146:149], v[194:197], v[108:111]
	v_mfma_f32_16x16x32_bf16 v[104:107], v[162:165], v[194:197], v[104:107]
	v_mfma_f32_16x16x32_bf16 v[92:95], v[146:149], v[202:205], v[92:95]
	v_mfma_f32_16x16x32_bf16 v[88:91], v[162:165], v[202:205], v[88:91]
	v_mfma_f32_16x16x32_bf16 v[76:79], v[146:149], v[210:213], v[76:79]
	v_mfma_f32_16x16x32_bf16 v[72:75], v[162:165], v[210:213], v[72:75]
	v_mfma_f32_16x16x32_bf16 v[124:127], v[158:161], v[190:193], v[124:127]
	v_mfma_f32_16x16x32_bf16 v[120:123], v[166:169], v[190:193], v[120:123]
	v_mfma_f32_16x16x32_bf16 v[108:111], v[158:161], v[198:201], v[108:111]
	v_mfma_f32_16x16x32_bf16 v[104:107], v[166:169], v[198:201], v[104:107]
	v_mfma_f32_16x16x32_bf16 v[92:95], v[158:161], v[206:209], v[92:95]
	v_mfma_f32_16x16x32_bf16 v[88:91], v[166:169], v[206:209], v[88:91]
	v_mfma_f32_16x16x32_bf16 v[76:79], v[158:161], v[214:217], v[76:79]
	v_mfma_f32_16x16x32_bf16 v[72:75], v[166:169], v[214:217], v[72:75]
	s_setprio 0
	s_setprio 1
	v_mfma_f32_16x16x32_bf16 v[116:119], v[170:173], v[186:189], v[116:119]
	v_mfma_f32_16x16x32_bf16 v[112:115], v[178:181], v[186:189], v[112:115]
	v_mfma_f32_16x16x32_bf16 v[100:103], v[170:173], v[194:197], v[100:103]
	v_mfma_f32_16x16x32_bf16 v[96:99], v[178:181], v[194:197], v[96:99]
	v_mfma_f32_16x16x32_bf16 v[84:87], v[170:173], v[202:205], v[84:87]
	v_mfma_f32_16x16x32_bf16 v[80:83], v[178:181], v[202:205], v[80:83]
	v_mfma_f32_16x16x32_bf16 v[68:71], v[170:173], v[210:213], v[68:71]
	v_mfma_f32_16x16x32_bf16 v[64:67], v[178:181], v[210:213], v[64:67]
	v_mfma_f32_16x16x32_bf16 v[116:119], v[174:177], v[190:193], v[116:119]
	v_mfma_f32_16x16x32_bf16 v[112:115], v[182:185], v[190:193], v[112:115]
	v_mfma_f32_16x16x32_bf16 v[100:103], v[174:177], v[198:201], v[100:103]
	v_mfma_f32_16x16x32_bf16 v[96:99], v[182:185], v[198:201], v[96:99]
	v_mfma_f32_16x16x32_bf16 v[84:87], v[174:177], v[206:209], v[84:87]
	v_mfma_f32_16x16x32_bf16 v[80:83], v[182:185], v[206:209], v[80:83]
	v_mfma_f32_16x16x32_bf16 v[68:71], v[174:177], v[214:217], v[68:71]
	v_mfma_f32_16x16x32_bf16 v[64:67], v[182:185], v[214:217], v[64:67]
	s_barrier
	s_setprio 0
	s_add_i32 s38, s72, s43
	v_lshl_add_u64 v[150:151], v[150:151], 0, s[12:13]
	s_mov_b32 m0, s38
	s_nop 0
	global_load_lds_dwordx4 v[150:151], off
	s_add_i32 m0, s38, 0x2000
	s_add_u32 s36, s36, 0x40080
	v_lshl_add_u64 v[150:151], v[218:219], 0, s[12:13]
	s_addc_u32 s37, s37, 0
	s_add_i32 s38, s73, s43
	global_load_lds_dwordx4 v[150:151], off
	v_lshl_add_u64 v[150:151], s[36:37], 0, v[130:131]
	s_mov_b32 m0, s38
	s_nop 0
	global_load_lds_dwordx4 v[150:151], off
	v_lshl_add_u64 v[150:151], s[36:37], 0, v[134:135]
	s_add_i32 m0, s38, 0x2000
	s_nop 0
	global_load_lds_dwordx4 v[150:151], off
	v_lshl_add_u64 v[150:151], v[220:221], 0, s[12:13]
	s_mov_b32 m0, s60
	s_nop 0
	global_load_lds_dwordx4 v[150:151], off
	v_lshl_add_u64 v[150:151], v[222:223], 0, s[12:13]
	s_mov_b32 m0, s61
	s_nop 0
	global_load_lds_dwordx4 v[150:151], off
	ds_read_b128 v[186:189], v157 offset:49152
	ds_read_b128 v[190:193], v157 offset:50176
	ds_read_b128 v[194:197], v157 offset:51200
	ds_read_b128 v[198:201], v157 offset:52224
	ds_read_b128 v[202:205], v157 offset:53248
	ds_read_b128 v[206:209], v157 offset:54272
	ds_read_b128 v[210:213], v157 offset:55296
	ds_read_b128 v[214:217], v157 offset:56320
	s_waitcnt vmcnt(8)
	s_waitcnt lgkmcnt(0)
	s_setprio 1
	s_barrier
	v_mfma_f32_16x16x32_bf16 v[60:63], v[146:149], v[186:189], v[60:63]
	v_mfma_f32_16x16x32_bf16 v[56:59], v[162:165], v[186:189], v[56:59]
	v_mfma_f32_16x16x32_bf16 v[44:47], v[146:149], v[194:197], v[44:47]
	v_mfma_f32_16x16x32_bf16 v[40:43], v[162:165], v[194:197], v[40:43]
	v_mfma_f32_16x16x32_bf16 v[28:31], v[146:149], v[202:205], v[28:31]
	v_mfma_f32_16x16x32_bf16 v[24:27], v[162:165], v[202:205], v[24:27]
	v_mfma_f32_16x16x32_bf16 v[12:15], v[146:149], v[210:213], v[12:15]
	v_mfma_f32_16x16x32_bf16 v[8:11], v[162:165], v[210:213], v[8:11]
	v_mfma_f32_16x16x32_bf16 v[60:63], v[158:161], v[190:193], v[60:63]
	v_mfma_f32_16x16x32_bf16 v[56:59], v[166:169], v[190:193], v[56:59]
	v_mfma_f32_16x16x32_bf16 v[44:47], v[158:161], v[198:201], v[44:47]
	v_mfma_f32_16x16x32_bf16 v[40:43], v[166:169], v[198:201], v[40:43]
	v_mfma_f32_16x16x32_bf16 v[28:31], v[158:161], v[206:209], v[28:31]
	v_mfma_f32_16x16x32_bf16 v[24:27], v[166:169], v[206:209], v[24:27]
	v_mfma_f32_16x16x32_bf16 v[12:15], v[158:161], v[214:217], v[12:15]
	v_mfma_f32_16x16x32_bf16 v[8:11], v[166:169], v[214:217], v[8:11]
	s_setprio 0
	s_setprio 1
	v_mfma_f32_16x16x32_bf16 v[52:55], v[170:173], v[186:189], v[52:55]
	v_mfma_f32_16x16x32_bf16 v[48:51], v[178:181], v[186:189], v[48:51]
	v_mfma_f32_16x16x32_bf16 v[36:39], v[170:173], v[194:197], v[36:39]
	v_mfma_f32_16x16x32_bf16 v[32:35], v[178:181], v[194:197], v[32:35]
	v_mfma_f32_16x16x32_bf16 v[20:23], v[170:173], v[202:205], v[20:23]
	v_mfma_f32_16x16x32_bf16 v[16:19], v[178:181], v[202:205], v[16:19]
	v_mfma_f32_16x16x32_bf16 v[4:7], v[170:173], v[210:213], v[4:7]
	v_mfma_f32_16x16x32_bf16 v[0:3], v[178:181], v[210:213], v[0:3]
	v_mfma_f32_16x16x32_bf16 v[52:55], v[174:177], v[190:193], v[52:55]
	v_mfma_f32_16x16x32_bf16 v[48:51], v[182:185], v[190:193], v[48:51]
	v_mfma_f32_16x16x32_bf16 v[36:39], v[174:177], v[198:201], v[36:39]
	v_mfma_f32_16x16x32_bf16 v[32:35], v[182:185], v[198:201], v[32:35]
	v_mfma_f32_16x16x32_bf16 v[20:23], v[174:177], v[206:209], v[20:23]
	v_mfma_f32_16x16x32_bf16 v[16:19], v[182:185], v[206:209], v[16:19]
	v_mfma_f32_16x16x32_bf16 v[4:7], v[174:177], v[214:217], v[4:7]
	v_mfma_f32_16x16x32_bf16 v[0:3], v[182:185], v[214:217], v[0:3]
	s_barrier
	s_setprio 0
	s_add_i32 s71, s71, 2
	s_add_u32 s34, s34, 0x100
	s_addc_u32 s35, s35, 0
	s_add_u32 s69, s69, 0x100
	s_addc_u32 s70, s70, 0
	s_cmp_gt_u32 s71, 13
	s_cbranch_scc0 .LBB0_217
	s_and_b64 vcc, exec, s[14:15]
	s_cbranch_vccz .LBB0_220
	s_barrier
	s_setprio 1

.LBB0_255:
	s_setprio 0
	s_waitcnt vmcnt(0)
	s_barrier

.Lph471_w:
	s_nop 0
	s_nop 0
	s_nop 0
	s_waitcnt vmcnt(8)
	s_waitcnt lgkmcnt(0)
	s_setprio 1
	s_barrier
	v_mfma_f32_16x16x32_bf16 v[124:127], v[128:131], v[160:163], v[124:127]
	v_mfma_f32_16x16x32_bf16 v[120:123], v[136:139], v[160:163], v[120:123]
	v_mfma_f32_16x16x32_bf16 v[108:111], v[128:131], v[168:171], v[108:111]
	v_mfma_f32_16x16x32_bf16 v[104:107], v[136:139], v[168:171], v[104:107]
	v_mfma_f32_16x16x32_bf16 v[92:95], v[128:131], v[192:195], v[92:95]
	v_mfma_f32_16x16x32_bf16 v[88:91], v[136:139], v[192:195], v[88:91]
	v_mfma_f32_16x16x32_bf16 v[76:79], v[128:131], v[200:203], v[76:79]
	v_mfma_f32_16x16x32_bf16 v[72:75], v[136:139], v[200:203], v[72:75]
	v_mfma_f32_16x16x32_bf16 v[124:127], v[132:135], v[164:167], v[124:127]
	v_mfma_f32_16x16x32_bf16 v[120:123], v[140:143], v[164:167], v[120:123]
	v_mfma_f32_16x16x32_bf16 v[108:111], v[132:135], v[172:175], v[108:111]
	v_mfma_f32_16x16x32_bf16 v[104:107], v[140:143], v[172:175], v[104:107]
	v_mfma_f32_16x16x32_bf16 v[92:95], v[132:135], v[196:199], v[92:95]
	v_mfma_f32_16x16x32_bf16 v[88:91], v[140:143], v[196:199], v[88:91]
	v_mfma_f32_16x16x32_bf16 v[76:79], v[132:135], v[210:213], v[76:79]
	v_mfma_f32_16x16x32_bf16 v[72:75], v[140:143], v[210:213], v[72:75]
	s_setprio 0
	s_setprio 1
	v_mfma_f32_16x16x32_bf16 v[116:119], v[144:147], v[160:163], v[116:119]
	v_mfma_f32_16x16x32_bf16 v[112:115], v[152:155], v[160:163], v[112:115]
	v_mfma_f32_16x16x32_bf16 v[100:103], v[144:147], v[168:171], v[100:103]
	v_mfma_f32_16x16x32_bf16 v[96:99], v[152:155], v[168:171], v[96:99]
	v_mfma_f32_16x16x32_bf16 v[84:87], v[144:147], v[192:195], v[84:87]
	v_mfma_f32_16x16x32_bf16 v[80:83], v[152:155], v[192:195], v[80:83]
	v_mfma_f32_16x16x32_bf16 v[68:71], v[144:147], v[200:203], v[68:71]
	v_mfma_f32_16x16x32_bf16 v[64:67], v[152:155], v[200:203], v[64:67]
	v_mfma_f32_16x16x32_bf16 v[116:119], v[148:151], v[164:167], v[116:119]
	v_mfma_f32_16x16x32_bf16 v[112:115], v[156:159], v[164:167], v[112:115]
	v_mfma_f32_16x16x32_bf16 v[100:103], v[148:151], v[172:175], v[100:103]
	v_mfma_f32_16x16x32_bf16 v[96:99], v[156:159], v[172:175], v[96:99]
	v_mfma_f32_16x16x32_bf16 v[84:87], v[148:151], v[196:199], v[84:87]
	v_mfma_f32_16x16x32_bf16 v[80:83], v[156:159], v[196:199], v[80:83]
	v_mfma_f32_16x16x32_bf16 v[68:71], v[148:151], v[210:213], v[68:71]
	v_mfma_f32_16x16x32_bf16 v[64:67], v[156:159], v[210:213], v[64:67]
	s_barrier
	s_setprio 0
	s_add_i32 s70, s62, s40
	v_lshl_add_u64 v[214:215], s[34:35], 0, v[178:179]
	s_mov_b32 m0, s70
	s_nop 0
	global_load_lds_dwordx4 v[214:215], off
	s_add_i32 m0, s70, 0x2000
	s_add_u32 s70, s34, 0x40000
	v_lshl_add_u64 v[216:217], s[34:35], 0, v[182:183]
	s_addc_u32 s71, s35, 0
	s_add_i32 s72, s63, s40
	global_load_lds_dwordx4 v[216:217], off
	v_lshl_add_u64 v[218:219], s[70:71], 0, v[178:179]
	s_mov_b32 m0, s72
	v_lshl_add_u64 v[220:221], s[36:37], 0, v[180:181]
	global_load_lds_dwordx4 v[218:219], off
	v_lshl_add_u64 v[218:219], s[70:71], 0, v[182:183]
	s_add_i32 m0, s72, 0x2000
	s_nop 0
	global_load_lds_dwordx4 v[218:219], off
	v_lshl_add_u64 v[218:219], s[36:37], 0, v[176:177]
	s_mov_b32 m0, s29
	s_nop 0
	global_load_lds_dwordx4 v[218:219], off
	s_mov_b32 m0, s41
	s_nop 0
	global_load_lds_dwordx4 v[220:221], off
	ds_read_b128 v[160:163], v209 offset:16384
	ds_read_b128 v[164:167], v209 offset:17408
	ds_read_b128 v[168:171], v209 offset:18432
	ds_read_b128 v[172:175], v209 offset:19456
	ds_read_b128 v[192:195], v209 offset:20480
	ds_read_b128 v[196:199], v209 offset:21504
	ds_read_b128 v[200:203], v209 offset:22528
	ds_read_b128 v[210:213], v209 offset:23552
	s_nop 0
	s_waitcnt vmcnt(8)
	s_waitcnt lgkmcnt(0)
	s_setprio 1
	s_barrier
	v_mfma_f32_16x16x32_bf16 v[60:63], v[128:131], v[160:163], v[60:63]
	v_mfma_f32_16x16x32_bf16 v[56:59], v[136:139], v[160:163], v[56:59]
	v_mfma_f32_16x16x32_bf16 v[44:47], v[128:131], v[168:171], v[44:47]
	v_mfma_f32_16x16x32_bf16 v[40:43], v[136:139], v[168:171], v[40:43]
	v_mfma_f32_16x16x32_bf16 v[28:31], v[128:131], v[192:195], v[28:31]
	v_mfma_f32_16x16x32_bf16 v[24:27], v[136:139], v[192:195], v[24:27]
	v_mfma_f32_16x16x32_bf16 v[12:15], v[128:131], v[200:203], v[12:15]
	v_mfma_f32_16x16x32_bf16 v[8:11], v[136:139], v[200:203], v[8:11]
	v_mfma_f32_16x16x32_bf16 v[60:63], v[132:135], v[164:167], v[60:63]
	v_mfma_f32_16x16x32_bf16 v[56:59], v[140:143], v[164:167], v[56:59]
	v_mfma_f32_16x16x32_bf16 v[44:47], v[132:135], v[172:175], v[44:47]
	v_mfma_f32_16x16x32_bf16 v[40:43], v[140:143], v[172:175], v[40:43]
	v_mfma_f32_16x16x32_bf16 v[28:31], v[132:135], v[196:199], v[28:31]
	v_mfma_f32_16x16x32_bf16 v[24:27], v[140:143], v[196:199], v[24:27]
	v_mfma_f32_16x16x32_bf16 v[12:15], v[132:135], v[210:213], v[12:15]
	v_mfma_f32_16x16x32_bf16 v[8:11], v[140:143], v[210:213], v[8:11]
	s_setprio 0
	s_setprio 1
	v_mfma_f32_16x16x32_bf16 v[52:55], v[144:147], v[160:163], v[52:55]
	v_mfma_f32_16x16x32_bf16 v[48:51], v[152:155], v[160:163], v[48:51]
	v_mfma_f32_16x16x32_bf16 v[36:39], v[144:147], v[168:171], v[36:39]
	v_mfma_f32_16x16x32_bf16 v[32:35], v[152:155], v[168:171], v[32:35]
	v_mfma_f32_16x16x32_bf16 v[20:23], v[144:147], v[192:195], v[20:23]
	v_mfma_f32_16x16x32_bf16 v[16:19], v[152:155], v[192:195], v[16:19]
	v_mfma_f32_16x16x32_bf16 v[4:7], v[144:147], v[200:203], v[4:7]
	v_mfma_f32_16x16x32_bf16 v[0:3], v[152:155], v[200:203], v[0:3]
	v_mfma_f32_16x16x32_bf16 v[52:55], v[148:151], v[164:167], v[52:55]
	v_mfma_f32_16x16x32_bf16 v[48:51], v[156:159], v[164:167], v[48:51]
	v_mfma_f32_16x16x32_bf16 v[36:39], v[148:151], v[172:175], v[36:39]
	v_mfma_f32_16x16x32_bf16 v[32:35], v[156:159], v[172:175], v[32:35]
	v_mfma_f32_16x16x32_bf16 v[20:23], v[148:151], v[196:199], v[20:23]
	v_mfma_f32_16x16x32_bf16 v[16:19], v[156:159], v[196:199], v[16:19]
	v_mfma_f32_16x16x32_bf16 v[4:7], v[148:151], v[210:213], v[4:7]
	v_mfma_f32_16x16x32_bf16 v[0:3], v[156:159], v[210:213], v[0:3]
	s_barrier
	s_setprio 0
	s_add_i32 s70, 0, 0x18000
	s_add_i32 s71, 0, 0x1c000
	s_add_u32 s36, s36, 0x40000
	s_addc_u32 s37, s37, 0
	s_mov_b32 m0, s42
	v_lshl_add_u64 v[222:223], s[36:37], 0, v[176:177]
	global_load_lds_dwordx4 v[222:223], off
	v_lshl_add_u64 v[222:223], s[36:37], 0, v[180:181]
	s_mov_b32 m0, s43
	s_nop 0
	global_load_lds_dwordx4 v[222:223], off
	v_add_u32_e32 v140, s70, v206
	v_add_u32_e32 v156, s71, v206
	ds_read_b128 v[128:131], v140
	ds_read_b128 v[132:135], v140 offset:1024
	ds_read_b128 v[136:139], v140 offset:2048
	ds_read_b128 v[140:143], v140 offset:3072
	ds_read_b128 v[144:147], v156
	ds_read_b128 v[148:151], v156 offset:1024
	ds_read_b128 v[152:155], v156 offset:2048
	ds_read_b128 v[156:159], v156 offset:3072
	ds_read_b128 v[160:163], v209 offset:32768
	ds_read_b128 v[164:167], v209 offset:33792
	ds_read_b128 v[168:171], v209 offset:34816
	ds_read_b128 v[172:175], v209 offset:35840
	ds_read_b128 v[192:195], v209 offset:36864
	ds_read_b128 v[196:199], v209 offset:37888
	ds_read_b128 v[200:203], v209 offset:38912
	ds_read_b128 v[210:213], v209 offset:39936
	s_waitcnt vmcnt(8)
	s_waitcnt lgkmcnt(0)
	s_setprio 1
	s_barrier
	v_mfma_f32_16x16x32_bf16 v[124:127], v[128:131], v[160:163], v[124:127]
	v_mfma_f32_16x16x32_bf16 v[120:123], v[136:139], v[160:163], v[120:123]
	v_mfma_f32_16x16x32_bf16 v[108:111], v[128:131], v[168:171], v[108:111]
	v_mfma_f32_16x16x32_bf16 v[104:107], v[136:139], v[168:171], v[104:107]
	v_mfma_f32_16x16x32_bf16 v[92:95], v[128:131], v[192:195], v[92:95]
	v_mfma_f32_16x16x32_bf16 v[88:91], v[136:139], v[192:195], v[88:91]
	v_mfma_f32_16x16x32_bf16 v[76:79], v[128:131], v[200:203], v[76:79]
	v_mfma_f32_16x16x32_bf16 v[72:75], v[136:139], v[200:203], v[72:75]
	v_mfma_f32_16x16x32_bf16 v[124:127], v[132:135], v[164:167], v[124:127]
	v_mfma_f32_16x16x32_bf16 v[120:123], v[140:143], v[164:167], v[120:123]
	v_mfma_f32_16x16x32_bf16 v[108:111], v[132:135], v[172:175], v[108:111]
	v_mfma_f32_16x16x32_bf16 v[104:107], v[140:143], v[172:175], v[104:107]
	v_mfma_f32_16x16x32_bf16 v[92:95], v[132:135], v[196:199], v[92:95]
	v_mfma_f32_16x16x32_bf16 v[88:91], v[140:143], v[196:199], v[88:91]
	v_mfma_f32_16x16x32_bf16 v[76:79], v[132:135], v[210:213], v[76:79]
	v_mfma_f32_16x16x32_bf16 v[72:75], v[140:143], v[210:213], v[72:75]
	s_setprio 0
	s_setprio 1
	v_mfma_f32_16x16x32_bf16 v[116:119], v[144:147], v[160:163], v[116:119]
	v_mfma_f32_16x16x32_bf16 v[112:115], v[152:155], v[160:163], v[112:115]
	v_mfma_f32_16x16x32_bf16 v[100:103], v[144:147], v[168:171], v[100:103]
	v_mfma_f32_16x16x32_bf16 v[96:99], v[152:155], v[168:171], v[96:99]
	v_mfma_f32_16x16x32_bf16 v[84:87], v[144:147], v[192:195], v[84:87]
	v_mfma_f32_16x16x32_bf16 v[80:83], v[152:155], v[192:195], v[80:83]
	v_mfma_f32_16x16x32_bf16 v[68:71], v[144:147], v[200:203], v[68:71]
	v_mfma_f32_16x16x32_bf16 v[64:67], v[152:155], v[200:203], v[64:67]
	v_mfma_f32_16x16x32_bf16 v[116:119], v[148:151], v[164:167], v[116:119]
	v_mfma_f32_16x16x32_bf16 v[112:115], v[156:159], v[164:167], v[112:115]
	v_mfma_f32_16x16x32_bf16 v[100:103], v[148:151], v[172:175], v[100:103]
	v_mfma_f32_16x16x32_bf16 v[96:99], v[156:159], v[172:175], v[96:99]
	v_mfma_f32_16x16x32_bf16 v[84:87], v[148:151], v[196:199], v[84:87]
	v_mfma_f32_16x16x32_bf16 v[80:83], v[156:159], v[196:199], v[80:83]
	v_mfma_f32_16x16x32_bf16 v[68:71], v[148:151], v[210:213], v[68:71]
	v_mfma_f32_16x16x32_bf16 v[64:67], v[156:159], v[210:213], v[64:67]
	s_barrier
	s_setprio 0
	s_add_i32 s36, s70, s40
	v_lshl_add_u64 v[214:215], v[214:215], 0, s[14:15]
	s_mov_b32 m0, s36
	s_nop 0
	global_load_lds_dwordx4 v[214:215], off
	s_add_i32 m0, s36, 0x2000
	s_add_u32 s34, s34, 0x40080
	v_lshl_add_u64 v[214:215], v[216:217], 0, s[14:15]
	s_addc_u32 s35, s35, 0
	s_add_i32 s36, s71, s40
	global_load_lds_dwordx4 v[214:215], off
	v_lshl_add_u64 v[214:215], s[34:35], 0, v[178:179]
	s_mov_b32 m0, s36
	s_nop 0
	global_load_lds_dwordx4 v[214:215], off
	v_lshl_add_u64 v[214:215], s[34:35], 0, v[182:183]
	s_add_i32 m0, s36, 0x2000
	s_nop 0
	global_load_lds_dwordx4 v[214:215], off
	v_lshl_add_u64 v[214:215], v[218:219], 0, s[14:15]
	s_mov_b32 m0, s49
	s_nop 0
	global_load_lds_dwordx4 v[214:215], off
	v_lshl_add_u64 v[214:215], v[220:221], 0, s[14:15]
	s_mov_b32 m0, s50
	s_nop 0
	global_load_lds_dwordx4 v[214:215], off
	ds_read_b128 v[160:163], v209 offset:49152
	ds_read_b128 v[164:167], v209 offset:50176
	ds_read_b128 v[168:171], v209 offset:51200
	ds_read_b128 v[172:175], v209 offset:52224
	ds_read_b128 v[192:195], v209 offset:53248
	ds_read_b128 v[196:199], v209 offset:54272
	ds_read_b128 v[200:203], v209 offset:55296
	ds_read_b128 v[210:213], v209 offset:56320
	s_waitcnt vmcnt(8)
	s_waitcnt lgkmcnt(0)
	s_setprio 1
	s_barrier
	v_mfma_f32_16x16x32_bf16 v[60:63], v[128:131], v[160:163], v[60:63]
	v_mfma_f32_16x16x32_bf16 v[56:59], v[136:139], v[160:163], v[56:59]
	v_mfma_f32_16x16x32_bf16 v[44:47], v[128:131], v[168:171], v[44:47]
	v_mfma_f32_16x16x32_bf16 v[40:43], v[136:139], v[168:171], v[40:43]
	v_mfma_f32_16x16x32_bf16 v[28:31], v[128:131], v[192:195], v[28:31]
	v_mfma_f32_16x16x32_bf16 v[24:27], v[136:139], v[192:195], v[24:27]
	v_mfma_f32_16x16x32_bf16 v[12:15], v[128:131], v[200:203], v[12:15]
	v_mfma_f32_16x16x32_bf16 v[8:11], v[136:139], v[200:203], v[8:11]
	v_mfma_f32_16x16x32_bf16 v[60:63], v[132:135], v[164:167], v[60:63]
	v_mfma_f32_16x16x32_bf16 v[56:59], v[140:143], v[164:167], v[56:59]
	v_mfma_f32_16x16x32_bf16 v[44:47], v[132:135], v[172:175], v[44:47]
	v_mfma_f32_16x16x32_bf16 v[40:43], v[140:143], v[172:175], v[40:43]
	v_mfma_f32_16x16x32_bf16 v[28:31], v[132:135], v[196:199], v[28:31]
	v_mfma_f32_16x16x32_bf16 v[24:27], v[140:143], v[196:199], v[24:27]
	v_mfma_f32_16x16x32_bf16 v[12:15], v[132:135], v[210:213], v[12:15]
	v_mfma_f32_16x16x32_bf16 v[8:11], v[140:143], v[210:213], v[8:11]
	s_setprio 0
	s_setprio 1
	v_mfma_f32_16x16x32_bf16 v[52:55], v[144:147], v[160:163], v[52:55]
	v_mfma_f32_16x16x32_bf16 v[48:51], v[152:155], v[160:163], v[48:51]
	v_mfma_f32_16x16x32_bf16 v[36:39], v[144:147], v[168:171], v[36:39]
	v_mfma_f32_16x16x32_bf16 v[32:35], v[152:155], v[168:171], v[32:35]
	v_mfma_f32_16x16x32_bf16 v[20:23], v[144:147], v[192:195], v[20:23]
	v_mfma_f32_16x16x32_bf16 v[16:19], v[152:155], v[192:195], v[16:19]
	v_mfma_f32_16x16x32_bf16 v[4:7], v[144:147], v[200:203], v[4:7]
	v_mfma_f32_16x16x32_bf16 v[0:3], v[152:155], v[200:203], v[0:3]
	v_mfma_f32_16x16x32_bf16 v[52:55], v[148:151], v[164:167], v[52:55]
	v_mfma_f32_16x16x32_bf16 v[48:51], v[156:159], v[164:167], v[48:51]
	v_mfma_f32_16x16x32_bf16 v[36:39], v[148:151], v[172:175], v[36:39]
	v_mfma_f32_16x16x32_bf16 v[32:35], v[156:159], v[172:175], v[32:35]
	v_mfma_f32_16x16x32_bf16 v[20:23], v[148:151], v[196:199], v[20:23]
	v_mfma_f32_16x16x32_bf16 v[16:19], v[156:159], v[196:199], v[16:19]
	v_mfma_f32_16x16x32_bf16 v[4:7], v[148:151], v[210:213], v[4:7]
	v_mfma_f32_16x16x32_bf16 v[0:3], v[156:159], v[210:213], v[0:3]
	s_barrier
	s_setprio 0
	s_add_i32 s69, s69, 2
	s_add_u32 s30, s30, 0x100
	s_addc_u32 s31, s31, 0
	s_add_u32 s65, s65, 0x100
	s_addc_u32 s68, s68, 0
	s_cmp_gt_u32 s69, 13
	s_cbranch_scc0 .LBB0_471
	s_and_b64 vcc, exec, s[16:17]
	s_cbranch_vccz .LBB0_474
	s_barrier
	s_setprio 1

.Lph555_w:
	s_nop 0
	s_nop 0
	s_waitcnt vmcnt(8)
	s_waitcnt lgkmcnt(0)
	s_setprio 1
	s_barrier
	v_mfma_f32_16x16x32_bf16 v[116:119], v[154:157], v[186:189], v[116:119]
	v_mfma_f32_16x16x32_bf16 v[112:115], v[162:165], v[186:189], v[112:115]
	v_mfma_f32_16x16x32_bf16 v[108:111], v[154:157], v[194:197], v[108:111]
	v_mfma_f32_16x16x32_bf16 v[100:103], v[162:165], v[194:197], v[100:103]
	v_mfma_f32_16x16x32_bf16 v[92:95], v[154:157], v[202:205], v[92:95]
	v_mfma_f32_16x16x32_bf16 v[84:87], v[162:165], v[202:205], v[84:87]
	v_mfma_f32_16x16x32_bf16 v[76:79], v[154:157], v[210:213], v[76:79]
	v_mfma_f32_16x16x32_bf16 v[68:71], v[162:165], v[210:213], v[68:71]
	v_mfma_f32_16x16x32_bf16 v[116:119], v[158:161], v[190:193], v[116:119]
	v_mfma_f32_16x16x32_bf16 v[112:115], v[166:169], v[190:193], v[112:115]
	v_mfma_f32_16x16x32_bf16 v[108:111], v[158:161], v[198:201], v[108:111]
	v_mfma_f32_16x16x32_bf16 v[100:103], v[166:169], v[198:201], v[100:103]
	v_mfma_f32_16x16x32_bf16 v[92:95], v[158:161], v[206:209], v[92:95]
	v_mfma_f32_16x16x32_bf16 v[84:87], v[166:169], v[206:209], v[84:87]
	v_mfma_f32_16x16x32_bf16 v[76:79], v[158:161], v[214:217], v[76:79]
	v_mfma_f32_16x16x32_bf16 v[68:71], v[166:169], v[214:217], v[68:71]
	s_setprio 0
	s_setprio 1
	v_mfma_f32_16x16x32_bf16 v[124:127], v[170:173], v[186:189], v[124:127]
	v_mfma_f32_16x16x32_bf16 v[120:123], v[178:181], v[186:189], v[120:123]
	v_mfma_f32_16x16x32_bf16 v[104:107], v[170:173], v[194:197], v[104:107]
	v_mfma_f32_16x16x32_bf16 v[96:99], v[178:181], v[194:197], v[96:99]
	v_mfma_f32_16x16x32_bf16 v[88:91], v[170:173], v[202:205], v[88:91]
	v_mfma_f32_16x16x32_bf16 v[80:83], v[178:181], v[202:205], v[80:83]
	v_mfma_f32_16x16x32_bf16 v[72:75], v[170:173], v[210:213], v[72:75]
	v_mfma_f32_16x16x32_bf16 v[64:67], v[178:181], v[210:213], v[64:67]
	v_mfma_f32_16x16x32_bf16 v[124:127], v[174:177], v[190:193], v[124:127]
	v_mfma_f32_16x16x32_bf16 v[120:123], v[182:185], v[190:193], v[120:123]
	v_mfma_f32_16x16x32_bf16 v[104:107], v[174:177], v[198:201], v[104:107]
	v_mfma_f32_16x16x32_bf16 v[96:99], v[182:185], v[198:201], v[96:99]
	v_mfma_f32_16x16x32_bf16 v[88:91], v[174:177], v[206:209], v[88:91]
	v_mfma_f32_16x16x32_bf16 v[80:83], v[182:185], v[206:209], v[80:83]
	v_mfma_f32_16x16x32_bf16 v[72:75], v[174:177], v[214:217], v[72:75]
	v_mfma_f32_16x16x32_bf16 v[64:67], v[182:185], v[214:217], v[64:67]
	s_barrier
	s_setprio 0
	s_add_i32 s64, s48, s36
	v_lshl_add_u64 v[144:145], s[30:31], 0, v[132:133]
	s_mov_b32 m0, s64
	s_nop 0
	global_load_lds_dwordx4 v[144:145], off
	s_add_i32 m0, s64, 0x2000
	s_add_u32 s64, s30, 0x40000
	v_lshl_add_u64 v[218:219], s[30:31], 0, v[128:129]
	s_addc_u32 s65, s31, 0
	s_add_i32 s68, s49, s36
	global_load_lds_dwordx4 v[218:219], off
	v_lshl_add_u64 v[220:221], s[64:65], 0, v[132:133]
	s_mov_b32 m0, s68
	v_lshl_add_u64 v[222:223], s[34:35], 0, v[130:131]
	global_load_lds_dwordx4 v[220:221], off
	v_lshl_add_u64 v[220:221], s[64:65], 0, v[128:129]
	s_add_i32 m0, s68, 0x2000
	s_nop 0
	global_load_lds_dwordx4 v[220:221], off
	v_lshl_add_u64 v[220:221], s[34:35], 0, v[134:135]
	s_mov_b32 m0, s25
	s_nop 0
	global_load_lds_dwordx4 v[220:221], off
	s_mov_b32 m0, s27
	s_nop 0
	global_load_lds_dwordx4 v[222:223], off
	ds_read_b128 v[186:189], v151 offset:16384
	ds_read_b128 v[190:193], v151 offset:17408
	ds_read_b128 v[194:197], v151 offset:18432
	ds_read_b128 v[198:201], v151 offset:19456
	ds_read_b128 v[202:205], v151 offset:20480
	ds_read_b128 v[206:209], v151 offset:21504
	ds_read_b128 v[210:213], v151 offset:22528
	ds_read_b128 v[214:217], v151 offset:23552
	s_nop 0
	s_waitcnt vmcnt(8)
	s_waitcnt lgkmcnt(0)
	s_setprio 1
	s_barrier
	v_mfma_f32_16x16x32_bf16 v[60:63], v[154:157], v[186:189], v[60:63]
	v_mfma_f32_16x16x32_bf16 v[52:55], v[162:165], v[186:189], v[52:55]
	v_mfma_f32_16x16x32_bf16 v[44:47], v[154:157], v[194:197], v[44:47]
	v_mfma_f32_16x16x32_bf16 v[36:39], v[162:165], v[194:197], v[36:39]
	v_mfma_f32_16x16x32_bf16 v[28:31], v[154:157], v[202:205], v[28:31]
	v_mfma_f32_16x16x32_bf16 v[20:23], v[162:165], v[202:205], v[20:23]
	v_mfma_f32_16x16x32_bf16 v[12:15], v[154:157], v[210:213], v[12:15]
	v_mfma_f32_16x16x32_bf16 v[4:7], v[162:165], v[210:213], v[4:7]
	v_mfma_f32_16x16x32_bf16 v[60:63], v[158:161], v[190:193], v[60:63]
	v_mfma_f32_16x16x32_bf16 v[52:55], v[166:169], v[190:193], v[52:55]
	v_mfma_f32_16x16x32_bf16 v[44:47], v[158:161], v[198:201], v[44:47]
	v_mfma_f32_16x16x32_bf16 v[36:39], v[166:169], v[198:201], v[36:39]
	v_mfma_f32_16x16x32_bf16 v[28:31], v[158:161], v[206:209], v[28:31]
	v_mfma_f32_16x16x32_bf16 v[20:23], v[166:169], v[206:209], v[20:23]
	v_mfma_f32_16x16x32_bf16 v[12:15], v[158:161], v[214:217], v[12:15]
	v_mfma_f32_16x16x32_bf16 v[4:7], v[166:169], v[214:217], v[4:7]
	s_setprio 0
	s_setprio 1
	v_mfma_f32_16x16x32_bf16 v[56:59], v[170:173], v[186:189], v[56:59]
	v_mfma_f32_16x16x32_bf16 v[48:51], v[178:181], v[186:189], v[48:51]
	v_mfma_f32_16x16x32_bf16 v[40:43], v[170:173], v[194:197], v[40:43]
	v_mfma_f32_16x16x32_bf16 v[32:35], v[178:181], v[194:197], v[32:35]
	v_mfma_f32_16x16x32_bf16 v[24:27], v[170:173], v[202:205], v[24:27]
	v_mfma_f32_16x16x32_bf16 v[16:19], v[178:181], v[202:205], v[16:19]
	v_mfma_f32_16x16x32_bf16 v[8:11], v[170:173], v[210:213], v[8:11]
	v_mfma_f32_16x16x32_bf16 v[0:3], v[178:181], v[210:213], v[0:3]
	v_mfma_f32_16x16x32_bf16 v[56:59], v[174:177], v[190:193], v[56:59]
	v_mfma_f32_16x16x32_bf16 v[48:51], v[182:185], v[190:193], v[48:51]
	v_mfma_f32_16x16x32_bf16 v[40:43], v[174:177], v[198:201], v[40:43]
	v_mfma_f32_16x16x32_bf16 v[32:35], v[182:185], v[198:201], v[32:35]
	v_mfma_f32_16x16x32_bf16 v[24:27], v[174:177], v[206:209], v[24:27]
	v_mfma_f32_16x16x32_bf16 v[16:19], v[182:185], v[206:209], v[16:19]
	v_mfma_f32_16x16x32_bf16 v[8:11], v[174:177], v[214:217], v[8:11]
	v_mfma_f32_16x16x32_bf16 v[0:3], v[182:185], v[214:217], v[0:3]
	s_barrier
	s_setprio 0
	s_add_i32 s64, 0, 0x18000
	s_add_i32 s65, 0, 0x1c000
	s_add_u32 s34, s34, 0x40000
	s_addc_u32 s35, s35, 0
	s_mov_b32 m0, s39
	v_lshl_add_u64 v[224:225], s[34:35], 0, v[134:135]
	global_load_lds_dwordx4 v[224:225], off
	v_lshl_add_u64 v[224:225], s[34:35], 0, v[130:131]
	s_mov_b32 m0, s40
	s_nop 0
	global_load_lds_dwordx4 v[224:225], off
	v_add_u32_e32 v153, s64, v147
	ds_read_b128 v[154:157], v153
	ds_read_b128 v[158:161], v153 offset:1024
	ds_read_b128 v[162:165], v153 offset:2048
	ds_read_b128 v[166:169], v153 offset:3072
	v_add_u32_e32 v153, s65, v147
	ds_read_b128 v[170:173], v153
	ds_read_b128 v[174:177], v153 offset:1024
	ds_read_b128 v[178:181], v153 offset:2048
	ds_read_b128 v[182:185], v153 offset:3072
	ds_read_b128 v[186:189], v151 offset:32768
	ds_read_b128 v[190:193], v151 offset:33792
	ds_read_b128 v[194:197], v151 offset:34816
	ds_read_b128 v[198:201], v151 offset:35840
	ds_read_b128 v[202:205], v151 offset:36864
	ds_read_b128 v[206:209], v151 offset:37888
	ds_read_b128 v[210:213], v151 offset:38912
	ds_read_b128 v[214:217], v151 offset:39936
	s_waitcnt vmcnt(8)
	s_waitcnt lgkmcnt(0)
	s_setprio 1
	s_barrier
	v_mfma_f32_16x16x32_bf16 v[116:119], v[154:157], v[186:189], v[116:119]
	v_mfma_f32_16x16x32_bf16 v[112:115], v[162:165], v[186:189], v[112:115]
	v_mfma_f32_16x16x32_bf16 v[108:111], v[154:157], v[194:197], v[108:111]
	v_mfma_f32_16x16x32_bf16 v[100:103], v[162:165], v[194:197], v[100:103]
	v_mfma_f32_16x16x32_bf16 v[92:95], v[154:157], v[202:205], v[92:95]
	v_mfma_f32_16x16x32_bf16 v[84:87], v[162:165], v[202:205], v[84:87]
	v_mfma_f32_16x16x32_bf16 v[76:79], v[154:157], v[210:213], v[76:79]
	v_mfma_f32_16x16x32_bf16 v[68:71], v[162:165], v[210:213], v[68:71]
	v_mfma_f32_16x16x32_bf16 v[116:119], v[158:161], v[190:193], v[116:119]
	v_mfma_f32_16x16x32_bf16 v[112:115], v[166:169], v[190:193], v[112:115]
	v_mfma_f32_16x16x32_bf16 v[108:111], v[158:161], v[198:201], v[108:111]
	v_mfma_f32_16x16x32_bf16 v[100:103], v[166:169], v[198:201], v[100:103]
	v_mfma_f32_16x16x32_bf16 v[92:95], v[158:161], v[206:209], v[92:95]
	v_mfma_f32_16x16x32_bf16 v[84:87], v[166:169], v[206:209], v[84:87]
	v_mfma_f32_16x16x32_bf16 v[76:79], v[158:161], v[214:217], v[76:79]
	v_mfma_f32_16x16x32_bf16 v[68:71], v[166:169], v[214:217], v[68:71]
	s_setprio 0
	s_setprio 1
	v_mfma_f32_16x16x32_bf16 v[124:127], v[170:173], v[186:189], v[124:127]
	v_mfma_f32_16x16x32_bf16 v[120:123], v[178:181], v[186:189], v[120:123]
	v_mfma_f32_16x16x32_bf16 v[104:107], v[170:173], v[194:197], v[104:107]
	v_mfma_f32_16x16x32_bf16 v[96:99], v[178:181], v[194:197], v[96:99]
	v_mfma_f32_16x16x32_bf16 v[88:91], v[170:173], v[202:205], v[88:91]
	v_mfma_f32_16x16x32_bf16 v[80:83], v[178:181], v[202:205], v[80:83]
	v_mfma_f32_16x16x32_bf16 v[72:75], v[170:173], v[210:213], v[72:75]
	v_mfma_f32_16x16x32_bf16 v[64:67], v[178:181], v[210:213], v[64:67]
	v_mfma_f32_16x16x32_bf16 v[124:127], v[174:177], v[190:193], v[124:127]
	v_mfma_f32_16x16x32_bf16 v[120:123], v[182:185], v[190:193], v[120:123]
	v_mfma_f32_16x16x32_bf16 v[104:107], v[174:177], v[198:201], v[104:107]
	v_mfma_f32_16x16x32_bf16 v[96:99], v[182:185], v[198:201], v[96:99]
	v_mfma_f32_16x16x32_bf16 v[88:91], v[174:177], v[206:209], v[88:91]
	v_mfma_f32_16x16x32_bf16 v[80:83], v[182:185], v[206:209], v[80:83]
	v_mfma_f32_16x16x32_bf16 v[72:75], v[174:177], v[214:217], v[72:75]
	v_mfma_f32_16x16x32_bf16 v[64:67], v[182:185], v[214:217], v[64:67]
	s_barrier
	s_setprio 0
	s_add_i32 s34, s64, s36
	v_lshl_add_u64 v[144:145], v[144:145], 0, s[12:13]
	s_mov_b32 m0, s34
	s_nop 0
	global_load_lds_dwordx4 v[144:145], off
	s_add_i32 m0, s34, 0x2000
	s_add_u32 s30, s30, 0x40080
	v_lshl_add_u64 v[144:145], v[218:219], 0, s[12:13]
	s_addc_u32 s31, s31, 0
	s_add_i32 s34, s65, s36
	global_load_lds_dwordx4 v[144:145], off
	v_lshl_add_u64 v[144:145], s[30:31], 0, v[132:133]
	s_mov_b32 m0, s34
	s_nop 0
	global_load_lds_dwordx4 v[144:145], off
	v_lshl_add_u64 v[144:145], s[30:31], 0, v[128:129]
	s_add_i32 m0, s34, 0x2000
	s_nop 0
	global_load_lds_dwordx4 v[144:145], off
	v_lshl_add_u64 v[144:145], v[220:221], 0, s[12:13]
	s_mov_b32 m0, s42
	s_nop 0
	global_load_lds_dwordx4 v[144:145], off
	v_lshl_add_u64 v[144:145], v[222:223], 0, s[12:13]
	s_mov_b32 m0, s43
	s_nop 0
	global_load_lds_dwordx4 v[144:145], off
	ds_read_b128 v[186:189], v151 offset:49152
	ds_read_b128 v[190:193], v151 offset:50176
	ds_read_b128 v[194:197], v151 offset:51200
	ds_read_b128 v[198:201], v151 offset:52224
	ds_read_b128 v[202:205], v151 offset:53248
	ds_read_b128 v[206:209], v151 offset:54272
	ds_read_b128 v[210:213], v151 offset:55296
	ds_read_b128 v[214:217], v151 offset:56320
	s_waitcnt vmcnt(8)
	s_waitcnt lgkmcnt(0)
	s_setprio 1
	s_barrier
	v_mfma_f32_16x16x32_bf16 v[60:63], v[154:157], v[186:189], v[60:63]
	v_mfma_f32_16x16x32_bf16 v[52:55], v[162:165], v[186:189], v[52:55]
	v_mfma_f32_16x16x32_bf16 v[44:47], v[154:157], v[194:197], v[44:47]
	v_mfma_f32_16x16x32_bf16 v[36:39], v[162:165], v[194:197], v[36:39]
	v_mfma_f32_16x16x32_bf16 v[28:31], v[154:157], v[202:205], v[28:31]
	v_mfma_f32_16x16x32_bf16 v[20:23], v[162:165], v[202:205], v[20:23]
	v_mfma_f32_16x16x32_bf16 v[12:15], v[154:157], v[210:213], v[12:15]
	v_mfma_f32_16x16x32_bf16 v[4:7], v[162:165], v[210:213], v[4:7]
	v_mfma_f32_16x16x32_bf16 v[60:63], v[158:161], v[190:193], v[60:63]
	v_mfma_f32_16x16x32_bf16 v[52:55], v[166:169], v[190:193], v[52:55]
	v_mfma_f32_16x16x32_bf16 v[44:47], v[158:161], v[198:201], v[44:47]
	v_mfma_f32_16x16x32_bf16 v[36:39], v[166:169], v[198:201], v[36:39]
	v_mfma_f32_16x16x32_bf16 v[28:31], v[158:161], v[206:209], v[28:31]
	v_mfma_f32_16x16x32_bf16 v[20:23], v[166:169], v[206:209], v[20:23]
	v_mfma_f32_16x16x32_bf16 v[12:15], v[158:161], v[214:217], v[12:15]
	v_mfma_f32_16x16x32_bf16 v[4:7], v[166:169], v[214:217], v[4:7]
	s_setprio 0
	s_setprio 1
	v_mfma_f32_16x16x32_bf16 v[56:59], v[170:173], v[186:189], v[56:59]
	v_mfma_f32_16x16x32_bf16 v[48:51], v[178:181], v[186:189], v[48:51]
	v_mfma_f32_16x16x32_bf16 v[40:43], v[170:173], v[194:197], v[40:43]
	v_mfma_f32_16x16x32_bf16 v[32:35], v[178:181], v[194:197], v[32:35]
	v_mfma_f32_16x16x32_bf16 v[24:27], v[170:173], v[202:205], v[24:27]
	v_mfma_f32_16x16x32_bf16 v[16:19], v[178:181], v[202:205], v[16:19]
	v_mfma_f32_16x16x32_bf16 v[8:11], v[170:173], v[210:213], v[8:11]
	v_mfma_f32_16x16x32_bf16 v[0:3], v[178:181], v[210:213], v[0:3]
	v_mfma_f32_16x16x32_bf16 v[56:59], v[174:177], v[190:193], v[56:59]
	v_mfma_f32_16x16x32_bf16 v[48:51], v[182:185], v[190:193], v[48:51]
	v_mfma_f32_16x16x32_bf16 v[40:43], v[174:177], v[198:201], v[40:43]
	v_mfma_f32_16x16x32_bf16 v[32:35], v[182:185], v[198:201], v[32:35]
	v_mfma_f32_16x16x32_bf16 v[24:27], v[174:177], v[206:209], v[24:27]
	v_mfma_f32_16x16x32_bf16 v[16:19], v[182:185], v[206:209], v[16:19]
	v_mfma_f32_16x16x32_bf16 v[8:11], v[174:177], v[214:217], v[8:11]
	v_mfma_f32_16x16x32_bf16 v[0:3], v[182:185], v[214:217], v[0:3]
	s_barrier
	s_setprio 0
	s_add_i32 s63, s63, 2
	s_add_u32 s28, s28, 0x100
	s_addc_u32 s29, s29, 0
	s_add_u32 s61, s61, 0x100
	s_addc_u32 s62, s62, 0
	s_cmp_gt_u32 s63, 13
	s_cbranch_scc0 .LBB0_555
	s_and_b64 vcc, exec, s[14:15]
	s_cbranch_vccz .LBB0_558
	s_barrier
	s_setprio 1

.Lph637_w:
	s_nop 0
	s_nop 0
	s_waitcnt vmcnt(8)
	s_waitcnt lgkmcnt(0)
	s_setprio 1
	s_barrier
	v_mfma_f32_16x16x32_bf16 v[144:147], v[120:123], v[160:163], v[144:147]
	v_mfma_f32_16x16x32_bf16 v[136:139], v[128:131], v[160:163], v[136:139]
	v_mfma_f32_16x16x32_bf16 v[108:111], v[120:123], v[168:171], v[108:111]
	v_mfma_f32_16x16x32_bf16 v[104:107], v[128:131], v[168:171], v[104:107]
	v_mfma_f32_16x16x32_bf16 v[92:95], v[120:123], v[176:179], v[92:95]
	v_mfma_f32_16x16x32_bf16 v[88:91], v[128:131], v[176:179], v[88:91]
	v_mfma_f32_16x16x32_bf16 v[76:79], v[120:123], v[184:187], v[76:79]
	v_mfma_f32_16x16x32_bf16 v[72:75], v[128:131], v[184:187], v[72:75]
	v_mfma_f32_16x16x32_bf16 v[144:147], v[124:127], v[164:167], v[144:147]
	v_mfma_f32_16x16x32_bf16 v[136:139], v[132:135], v[164:167], v[136:139]
	v_mfma_f32_16x16x32_bf16 v[108:111], v[124:127], v[172:175], v[108:111]
	v_mfma_f32_16x16x32_bf16 v[104:107], v[132:135], v[172:175], v[104:107]
	v_mfma_f32_16x16x32_bf16 v[92:95], v[124:127], v[180:183], v[92:95]
	v_mfma_f32_16x16x32_bf16 v[88:91], v[132:135], v[180:183], v[88:91]
	v_mfma_f32_16x16x32_bf16 v[76:79], v[124:127], v[188:191], v[76:79]
	v_mfma_f32_16x16x32_bf16 v[72:75], v[132:135], v[188:191], v[72:75]
	s_setprio 0
	s_setprio 1
	v_mfma_f32_16x16x32_bf16 v[116:119], v[140:143], v[160:163], v[116:119]
	v_mfma_f32_16x16x32_bf16 v[112:115], v[152:155], v[160:163], v[112:115]
	v_mfma_f32_16x16x32_bf16 v[100:103], v[140:143], v[168:171], v[100:103]
	v_mfma_f32_16x16x32_bf16 v[96:99], v[152:155], v[168:171], v[96:99]
	v_mfma_f32_16x16x32_bf16 v[84:87], v[140:143], v[176:179], v[84:87]
	v_mfma_f32_16x16x32_bf16 v[80:83], v[152:155], v[176:179], v[80:83]
	v_mfma_f32_16x16x32_bf16 v[68:71], v[140:143], v[184:187], v[68:71]
	v_mfma_f32_16x16x32_bf16 v[64:67], v[152:155], v[184:187], v[64:67]
	v_mfma_f32_16x16x32_bf16 v[116:119], v[148:151], v[164:167], v[116:119]
	v_mfma_f32_16x16x32_bf16 v[112:115], v[156:159], v[164:167], v[112:115]
	v_mfma_f32_16x16x32_bf16 v[100:103], v[148:151], v[172:175], v[100:103]
	v_mfma_f32_16x16x32_bf16 v[96:99], v[156:159], v[172:175], v[96:99]
	v_mfma_f32_16x16x32_bf16 v[84:87], v[148:151], v[180:183], v[84:87]
	v_mfma_f32_16x16x32_bf16 v[80:83], v[156:159], v[180:183], v[80:83]
	v_mfma_f32_16x16x32_bf16 v[68:71], v[148:151], v[188:191], v[68:71]
	v_mfma_f32_16x16x32_bf16 v[64:67], v[156:159], v[188:191], v[64:67]
	s_barrier
	s_setprio 0
	s_add_i32 s20, s43, s28
	v_lshl_add_u64 v[206:207], s[24:25], 0, v[194:195]
	s_mov_b32 m0, s20
	s_nop 0
	global_load_lds_dwordx4 v[206:207], off
	s_add_i32 m0, s20, 0x2000
	s_add_u32 s20, s24, 0xb0000
	v_lshl_add_u64 v[208:209], s[24:25], 0, v[198:199]
	s_addc_u32 s21, s25, 0
	s_add_i32 s62, s46, s28
	global_load_lds_dwordx4 v[208:209], off
	v_lshl_add_u64 v[210:211], s[20:21], 0, v[194:195]
	s_mov_b32 m0, s62
	v_lshl_add_u64 v[212:213], s[26:27], 0, v[196:197]
	global_load_lds_dwordx4 v[210:211], off
	v_lshl_add_u64 v[210:211], s[20:21], 0, v[198:199]
	s_add_i32 m0, s62, 0x2000
	s_nop 0
	global_load_lds_dwordx4 v[210:211], off
	v_lshl_add_u64 v[210:211], s[26:27], 0, v[192:193]
	s_mov_b32 m0, s29
	s_nop 0
	global_load_lds_dwordx4 v[210:211], off
	s_mov_b32 m0, s30
	s_nop 0
	global_load_lds_dwordx4 v[212:213], off
	ds_read_b128 v[160:163], v249 offset:16384
	ds_read_b128 v[164:167], v249 offset:17408
	ds_read_b128 v[168:171], v249 offset:18432
	ds_read_b128 v[172:175], v249 offset:19456
	ds_read_b128 v[176:179], v249 offset:20480
	ds_read_b128 v[180:183], v249 offset:21504
	ds_read_b128 v[184:187], v249 offset:22528
	ds_read_b128 v[188:191], v249 offset:23552
	s_nop 0
	s_waitcnt vmcnt(8)
	s_waitcnt lgkmcnt(0)
	s_setprio 1
	s_barrier
	v_mfma_f32_16x16x32_bf16 v[60:63], v[120:123], v[160:163], v[60:63]
	v_mfma_f32_16x16x32_bf16 v[56:59], v[128:131], v[160:163], v[56:59]
	v_mfma_f32_16x16x32_bf16 v[44:47], v[120:123], v[168:171], v[44:47]
	v_mfma_f32_16x16x32_bf16 v[40:43], v[128:131], v[168:171], v[40:43]
	v_mfma_f32_16x16x32_bf16 v[28:31], v[120:123], v[176:179], v[28:31]
	v_mfma_f32_16x16x32_bf16 v[24:27], v[128:131], v[176:179], v[24:27]
	v_mfma_f32_16x16x32_bf16 v[12:15], v[120:123], v[184:187], v[12:15]
	v_mfma_f32_16x16x32_bf16 v[8:11], v[128:131], v[184:187], v[8:11]
	v_mfma_f32_16x16x32_bf16 v[60:63], v[124:127], v[164:167], v[60:63]
	v_mfma_f32_16x16x32_bf16 v[56:59], v[132:135], v[164:167], v[56:59]
	v_mfma_f32_16x16x32_bf16 v[44:47], v[124:127], v[172:175], v[44:47]
	v_mfma_f32_16x16x32_bf16 v[40:43], v[132:135], v[172:175], v[40:43]
	v_mfma_f32_16x16x32_bf16 v[28:31], v[124:127], v[180:183], v[28:31]
	v_mfma_f32_16x16x32_bf16 v[24:27], v[132:135], v[180:183], v[24:27]
	v_mfma_f32_16x16x32_bf16 v[12:15], v[124:127], v[188:191], v[12:15]
	v_mfma_f32_16x16x32_bf16 v[8:11], v[132:135], v[188:191], v[8:11]
	s_setprio 0
	s_setprio 1
	v_mfma_f32_16x16x32_bf16 v[52:55], v[140:143], v[160:163], v[52:55]
	v_mfma_f32_16x16x32_bf16 v[48:51], v[152:155], v[160:163], v[48:51]
	v_mfma_f32_16x16x32_bf16 v[36:39], v[140:143], v[168:171], v[36:39]
	v_mfma_f32_16x16x32_bf16 v[32:35], v[152:155], v[168:171], v[32:35]
	v_mfma_f32_16x16x32_bf16 v[20:23], v[140:143], v[176:179], v[20:23]
	v_mfma_f32_16x16x32_bf16 v[16:19], v[152:155], v[176:179], v[16:19]
	v_mfma_f32_16x16x32_bf16 v[4:7], v[140:143], v[184:187], v[4:7]
	v_mfma_f32_16x16x32_bf16 v[0:3], v[152:155], v[184:187], v[0:3]
	v_mfma_f32_16x16x32_bf16 v[52:55], v[148:151], v[164:167], v[52:55]
	v_mfma_f32_16x16x32_bf16 v[48:51], v[156:159], v[164:167], v[48:51]
	v_mfma_f32_16x16x32_bf16 v[36:39], v[148:151], v[172:175], v[36:39]
	v_mfma_f32_16x16x32_bf16 v[32:35], v[156:159], v[172:175], v[32:35]
	v_mfma_f32_16x16x32_bf16 v[20:23], v[148:151], v[180:183], v[20:23]
	v_mfma_f32_16x16x32_bf16 v[16:19], v[156:159], v[180:183], v[16:19]
	v_mfma_f32_16x16x32_bf16 v[4:7], v[148:151], v[188:191], v[4:7]
	v_mfma_f32_16x16x32_bf16 v[0:3], v[156:159], v[188:191], v[0:3]
	s_barrier
	s_setprio 0
	s_add_i32 s62, 0, 0x18000
	s_add_i32 s63, 0, 0x1c000
	s_add_u32 s20, s26, 0xb0000
	s_addc_u32 s21, s27, 0
	s_mov_b32 m0, s31
	v_lshl_add_u64 v[214:215], s[20:21], 0, v[192:193]
	global_load_lds_dwordx4 v[214:215], off
	v_lshl_add_u64 v[214:215], s[20:21], 0, v[196:197]
	s_mov_b32 m0, s34
	s_nop 0
	global_load_lds_dwordx4 v[214:215], off
	v_add_u32_e32 v132, s62, v246
	v_add_u32_e32 v156, s63, v246
	ds_read_b128 v[120:123], v132
	ds_read_b128 v[124:127], v132 offset:1024
	ds_read_b128 v[128:131], v132 offset:2048
	ds_read_b128 v[132:135], v132 offset:3072
	ds_read_b128 v[140:143], v156
	ds_read_b128 v[148:151], v156 offset:1024
	ds_read_b128 v[152:155], v156 offset:2048
	ds_read_b128 v[156:159], v156 offset:3072
	ds_read_b128 v[160:163], v249 offset:32768
	ds_read_b128 v[164:167], v249 offset:33792
	ds_read_b128 v[168:171], v249 offset:34816
	ds_read_b128 v[172:175], v249 offset:35840
	ds_read_b128 v[176:179], v249 offset:36864
	ds_read_b128 v[180:183], v249 offset:37888
	ds_read_b128 v[184:187], v249 offset:38912
	ds_read_b128 v[188:191], v249 offset:39936
	s_waitcnt vmcnt(8)
	s_waitcnt lgkmcnt(0)
	s_setprio 1
	s_barrier
	v_mfma_f32_16x16x32_bf16 v[144:147], v[120:123], v[160:163], v[144:147]
	v_mfma_f32_16x16x32_bf16 v[136:139], v[128:131], v[160:163], v[136:139]
	v_mfma_f32_16x16x32_bf16 v[108:111], v[120:123], v[168:171], v[108:111]
	v_mfma_f32_16x16x32_bf16 v[104:107], v[128:131], v[168:171], v[104:107]
	v_mfma_f32_16x16x32_bf16 v[92:95], v[120:123], v[176:179], v[92:95]
	v_mfma_f32_16x16x32_bf16 v[88:91], v[128:131], v[176:179], v[88:91]
	v_mfma_f32_16x16x32_bf16 v[76:79], v[120:123], v[184:187], v[76:79]
	v_mfma_f32_16x16x32_bf16 v[72:75], v[128:131], v[184:187], v[72:75]
	v_mfma_f32_16x16x32_bf16 v[144:147], v[124:127], v[164:167], v[144:147]
	v_mfma_f32_16x16x32_bf16 v[136:139], v[132:135], v[164:167], v[136:139]
	v_mfma_f32_16x16x32_bf16 v[108:111], v[124:127], v[172:175], v[108:111]
	v_mfma_f32_16x16x32_bf16 v[104:107], v[132:135], v[172:175], v[104:107]
	v_mfma_f32_16x16x32_bf16 v[92:95], v[124:127], v[180:183], v[92:95]
	v_mfma_f32_16x16x32_bf16 v[88:91], v[132:135], v[180:183], v[88:91]
	v_mfma_f32_16x16x32_bf16 v[76:79], v[124:127], v[188:191], v[76:79]
	v_mfma_f32_16x16x32_bf16 v[72:75], v[132:135], v[188:191], v[72:75]
	s_setprio 0
	s_setprio 1
	v_mfma_f32_16x16x32_bf16 v[116:119], v[140:143], v[160:163], v[116:119]
	v_mfma_f32_16x16x32_bf16 v[112:115], v[152:155], v[160:163], v[112:115]
	v_mfma_f32_16x16x32_bf16 v[100:103], v[140:143], v[168:171], v[100:103]
	v_mfma_f32_16x16x32_bf16 v[96:99], v[152:155], v[168:171], v[96:99]
	v_mfma_f32_16x16x32_bf16 v[84:87], v[140:143], v[176:179], v[84:87]
	v_mfma_f32_16x16x32_bf16 v[80:83], v[152:155], v[176:179], v[80:83]
	v_mfma_f32_16x16x32_bf16 v[68:71], v[140:143], v[184:187], v[68:71]
	v_mfma_f32_16x16x32_bf16 v[64:67], v[152:155], v[184:187], v[64:67]
	v_mfma_f32_16x16x32_bf16 v[116:119], v[148:151], v[164:167], v[116:119]
	v_mfma_f32_16x16x32_bf16 v[112:115], v[156:159], v[164:167], v[112:115]
	v_mfma_f32_16x16x32_bf16 v[100:103], v[148:151], v[172:175], v[100:103]
	v_mfma_f32_16x16x32_bf16 v[96:99], v[156:159], v[172:175], v[96:99]
	v_mfma_f32_16x16x32_bf16 v[84:87], v[148:151], v[180:183], v[84:87]
	v_mfma_f32_16x16x32_bf16 v[80:83], v[156:159], v[180:183], v[80:83]
	v_mfma_f32_16x16x32_bf16 v[68:71], v[148:151], v[188:191], v[68:71]
	v_mfma_f32_16x16x32_bf16 v[64:67], v[156:159], v[188:191], v[64:67]
	s_barrier
	s_setprio 0
	s_add_i32 s20, s62, s28
	v_lshl_add_u64 v[206:207], v[206:207], 0, s[14:15]
	s_mov_b32 m0, s20
	s_nop 0
	global_load_lds_dwordx4 v[206:207], off
	s_add_i32 m0, s20, 0x2000
	s_add_u32 s20, s24, 0xb0080
	v_lshl_add_u64 v[206:207], v[208:209], 0, s[14:15]
	s_addc_u32 s21, s25, 0
	s_add_i32 s24, s63, s28
	global_load_lds_dwordx4 v[206:207], off
	v_lshl_add_u64 v[206:207], s[20:21], 0, v[194:195]
	s_mov_b32 m0, s24
	s_nop 0
	global_load_lds_dwordx4 v[206:207], off
	v_lshl_add_u64 v[206:207], s[20:21], 0, v[198:199]
	s_add_i32 m0, s24, 0x2000
	s_nop 0
	global_load_lds_dwordx4 v[206:207], off
	v_lshl_add_u64 v[206:207], v[210:211], 0, s[14:15]
	s_mov_b32 m0, s38
	s_nop 0
	global_load_lds_dwordx4 v[206:207], off
	v_lshl_add_u64 v[206:207], v[212:213], 0, s[14:15]
	s_mov_b32 m0, s39
	s_nop 0
	global_load_lds_dwordx4 v[206:207], off
	ds_read_b128 v[160:163], v249 offset:49152
	ds_read_b128 v[164:167], v249 offset:50176
	ds_read_b128 v[168:171], v249 offset:51200
	ds_read_b128 v[172:175], v249 offset:52224
	ds_read_b128 v[176:179], v249 offset:53248
	ds_read_b128 v[180:183], v249 offset:54272
	ds_read_b128 v[184:187], v249 offset:55296
	ds_read_b128 v[188:191], v249 offset:56320
	s_waitcnt vmcnt(8)
	s_waitcnt lgkmcnt(0)
	s_setprio 1
	s_barrier
	v_mfma_f32_16x16x32_bf16 v[60:63], v[120:123], v[160:163], v[60:63]
	v_mfma_f32_16x16x32_bf16 v[56:59], v[128:131], v[160:163], v[56:59]
	v_mfma_f32_16x16x32_bf16 v[44:47], v[120:123], v[168:171], v[44:47]
	v_mfma_f32_16x16x32_bf16 v[40:43], v[128:131], v[168:171], v[40:43]
	v_mfma_f32_16x16x32_bf16 v[28:31], v[120:123], v[176:179], v[28:31]
	v_mfma_f32_16x16x32_bf16 v[24:27], v[128:131], v[176:179], v[24:27]
	v_mfma_f32_16x16x32_bf16 v[12:15], v[120:123], v[184:187], v[12:15]
	v_mfma_f32_16x16x32_bf16 v[8:11], v[128:131], v[184:187], v[8:11]
	v_mfma_f32_16x16x32_bf16 v[60:63], v[124:127], v[164:167], v[60:63]
	v_mfma_f32_16x16x32_bf16 v[56:59], v[132:135], v[164:167], v[56:59]
	v_mfma_f32_16x16x32_bf16 v[44:47], v[124:127], v[172:175], v[44:47]
	v_mfma_f32_16x16x32_bf16 v[40:43], v[132:135], v[172:175], v[40:43]
	v_mfma_f32_16x16x32_bf16 v[28:31], v[124:127], v[180:183], v[28:31]
	v_mfma_f32_16x16x32_bf16 v[24:27], v[132:135], v[180:183], v[24:27]
	v_mfma_f32_16x16x32_bf16 v[12:15], v[124:127], v[188:191], v[12:15]
	v_mfma_f32_16x16x32_bf16 v[8:11], v[132:135], v[188:191], v[8:11]
	s_setprio 0
	s_setprio 1
	v_mfma_f32_16x16x32_bf16 v[52:55], v[140:143], v[160:163], v[52:55]
	v_mfma_f32_16x16x32_bf16 v[48:51], v[152:155], v[160:163], v[48:51]
	v_mfma_f32_16x16x32_bf16 v[36:39], v[140:143], v[168:171], v[36:39]
	v_mfma_f32_16x16x32_bf16 v[32:35], v[152:155], v[168:171], v[32:35]
	v_mfma_f32_16x16x32_bf16 v[20:23], v[140:143], v[176:179], v[20:23]
	v_mfma_f32_16x16x32_bf16 v[16:19], v[152:155], v[176:179], v[16:19]
	v_mfma_f32_16x16x32_bf16 v[4:7], v[140:143], v[184:187], v[4:7]
	v_mfma_f32_16x16x32_bf16 v[0:3], v[152:155], v[184:187], v[0:3]
	v_mfma_f32_16x16x32_bf16 v[52:55], v[148:151], v[164:167], v[52:55]
	v_mfma_f32_16x16x32_bf16 v[48:51], v[156:159], v[164:167], v[48:51]
	v_mfma_f32_16x16x32_bf16 v[36:39], v[148:151], v[172:175], v[36:39]
	v_mfma_f32_16x16x32_bf16 v[32:35], v[156:159], v[172:175], v[32:35]
	v_mfma_f32_16x16x32_bf16 v[20:23], v[148:151], v[180:183], v[20:23]
	v_mfma_f32_16x16x32_bf16 v[16:19], v[156:159], v[180:183], v[16:19]
	v_mfma_f32_16x16x32_bf16 v[4:7], v[148:151], v[188:191], v[4:7]
	v_mfma_f32_16x16x32_bf16 v[0:3], v[156:159], v[188:191], v[0:3]
	s_barrier
	s_setprio 0
	s_add_i32 s61, s61, 2
	s_add_u32 s51, s51, 0x100
	s_addc_u32 s60, s60, 0
	s_cmp_gt_u32 s61, 41
	s_mov_b64 s[20:21], s[22:23]
	s_cbranch_scc0 .LBB0_637
	s_and_b64 vcc, exec, s[16:17]
	s_cbranch_vccz .LBB0_640
	s_barrier
	s_setprio 1

.Lph723_w:
	s_nop 0
	s_nop 0
	s_waitcnt vmcnt(8)
	s_waitcnt lgkmcnt(0)
	s_setprio 1
	s_barrier
	v_mfma_f32_16x16x32_bf16 v[124:127], v[128:131], v[160:163], v[124:127]
	v_mfma_f32_16x16x32_bf16 v[120:123], v[136:139], v[160:163], v[120:123]
	v_mfma_f32_16x16x32_bf16 v[116:119], v[128:131], v[168:171], v[116:119]
	v_mfma_f32_16x16x32_bf16 v[112:115], v[136:139], v[168:171], v[112:115]
	v_mfma_f32_16x16x32_bf16 v[108:111], v[128:131], v[176:179], v[108:111]
	v_mfma_f32_16x16x32_bf16 v[100:103], v[136:139], v[176:179], v[100:103]
	v_mfma_f32_16x16x32_bf16 v[92:95], v[128:131], v[184:187], v[92:95]
	v_mfma_f32_16x16x32_bf16 v[80:83], v[136:139], v[184:187], v[80:83]
	v_mfma_f32_16x16x32_bf16 v[124:127], v[132:135], v[164:167], v[124:127]
	v_mfma_f32_16x16x32_bf16 v[120:123], v[140:143], v[164:167], v[120:123]
	v_mfma_f32_16x16x32_bf16 v[116:119], v[132:135], v[172:175], v[116:119]
	v_mfma_f32_16x16x32_bf16 v[112:115], v[140:143], v[172:175], v[112:115]
	v_mfma_f32_16x16x32_bf16 v[108:111], v[132:135], v[180:183], v[108:111]
	v_mfma_f32_16x16x32_bf16 v[100:103], v[140:143], v[180:183], v[100:103]
	v_mfma_f32_16x16x32_bf16 v[92:95], v[132:135], v[188:191], v[92:95]
	v_mfma_f32_16x16x32_bf16 v[80:83], v[140:143], v[188:191], v[80:83]
	s_setprio 0
	s_setprio 1
	v_mfma_f32_16x16x32_bf16 v[104:107], v[144:147], v[160:163], v[104:107]
	v_mfma_f32_16x16x32_bf16 v[96:99], v[152:155], v[160:163], v[96:99]
	v_mfma_f32_16x16x32_bf16 v[88:91], v[144:147], v[168:171], v[88:91]
	v_mfma_f32_16x16x32_bf16 v[84:87], v[152:155], v[168:171], v[84:87]
	v_mfma_f32_16x16x32_bf16 v[76:79], v[144:147], v[176:179], v[76:79]
	v_mfma_f32_16x16x32_bf16 v[72:75], v[152:155], v[176:179], v[72:75]
	v_mfma_f32_16x16x32_bf16 v[68:71], v[144:147], v[184:187], v[68:71]
	v_mfma_f32_16x16x32_bf16 v[64:67], v[152:155], v[184:187], v[64:67]
	v_mfma_f32_16x16x32_bf16 v[104:107], v[148:151], v[164:167], v[104:107]
	v_mfma_f32_16x16x32_bf16 v[96:99], v[156:159], v[164:167], v[96:99]
	v_mfma_f32_16x16x32_bf16 v[88:91], v[148:151], v[172:175], v[88:91]
	v_mfma_f32_16x16x32_bf16 v[84:87], v[156:159], v[172:175], v[84:87]
	v_mfma_f32_16x16x32_bf16 v[76:79], v[148:151], v[180:183], v[76:79]
	v_mfma_f32_16x16x32_bf16 v[72:75], v[156:159], v[180:183], v[72:75]
	v_mfma_f32_16x16x32_bf16 v[68:71], v[148:151], v[188:191], v[68:71]
	v_mfma_f32_16x16x32_bf16 v[64:67], v[156:159], v[188:191], v[64:67]
	s_barrier
	s_setprio 0
	s_add_i32 s94, s88, s68
	v_lshl_add_u64 v[192:193], s[62:63], 0, v[208:209]
	s_mov_b32 m0, s94
	s_nop 0
	global_load_lds_dwordx4 v[192:193], off
	s_add_i32 m0, s94, 0x2000
	s_add_u32 s94, s62, 0x40000
	v_lshl_add_u64 v[194:195], s[62:63], 0, v[212:213]
	s_addc_u32 s95, s63, 0
	s_add_i32 s96, s89, s68
	global_load_lds_dwordx4 v[194:195], off
	v_lshl_add_u64 v[196:197], s[94:95], 0, v[208:209]
	s_mov_b32 m0, s96
	v_lshl_add_u64 v[198:199], s[64:65], 0, v[210:211]
	global_load_lds_dwordx4 v[196:197], off
	v_lshl_add_u64 v[196:197], s[94:95], 0, v[212:213]
	s_add_i32 m0, s96, 0x2000
	s_nop 0
	global_load_lds_dwordx4 v[196:197], off
	v_lshl_add_u64 v[196:197], s[64:65], 0, v[206:207]
	s_mov_b32 m0, s69
	s_nop 0
	global_load_lds_dwordx4 v[196:197], off
	s_mov_b32 m0, s70
	s_nop 0
	global_load_lds_dwordx4 v[198:199], off
	ds_read_b128 v[160:163], v237 offset:16384
	ds_read_b128 v[164:167], v237 offset:17408
	ds_read_b128 v[168:171], v237 offset:18432
	ds_read_b128 v[172:175], v237 offset:19456
	ds_read_b128 v[176:179], v237 offset:20480
	ds_read_b128 v[180:183], v237 offset:21504
	ds_read_b128 v[184:187], v237 offset:22528
	ds_read_b128 v[188:191], v237 offset:23552
	s_nop 0
	s_waitcnt vmcnt(8)
	s_waitcnt lgkmcnt(0)
	s_setprio 1
	s_barrier
	v_mfma_f32_16x16x32_bf16 v[60:63], v[128:131], v[160:163], v[60:63]
	v_mfma_f32_16x16x32_bf16 v[56:59], v[136:139], v[160:163], v[56:59]
	v_mfma_f32_16x16x32_bf16 v[48:51], v[128:131], v[168:171], v[48:51]
	v_mfma_f32_16x16x32_bf16 v[40:43], v[136:139], v[168:171], v[40:43]
	v_mfma_f32_16x16x32_bf16 v[32:35], v[128:131], v[176:179], v[32:35]
	v_mfma_f32_16x16x32_bf16 v[24:27], v[136:139], v[176:179], v[24:27]
	v_mfma_f32_16x16x32_bf16 v[16:19], v[128:131], v[184:187], v[16:19]
	v_mfma_f32_16x16x32_bf16 v[8:11], v[136:139], v[184:187], v[8:11]
	v_mfma_f32_16x16x32_bf16 v[60:63], v[132:135], v[164:167], v[60:63]
	v_mfma_f32_16x16x32_bf16 v[56:59], v[140:143], v[164:167], v[56:59]
	v_mfma_f32_16x16x32_bf16 v[48:51], v[132:135], v[172:175], v[48:51]
	v_mfma_f32_16x16x32_bf16 v[40:43], v[140:143], v[172:175], v[40:43]
	v_mfma_f32_16x16x32_bf16 v[32:35], v[132:135], v[180:183], v[32:35]
	v_mfma_f32_16x16x32_bf16 v[24:27], v[140:143], v[180:183], v[24:27]
	v_mfma_f32_16x16x32_bf16 v[16:19], v[132:135], v[188:191], v[16:19]
	v_mfma_f32_16x16x32_bf16 v[8:11], v[140:143], v[188:191], v[8:11]
	s_setprio 0
	s_setprio 1
	v_mfma_f32_16x16x32_bf16 v[52:55], v[144:147], v[160:163], v[52:55]
	v_mfma_f32_16x16x32_bf16 v[44:47], v[152:155], v[160:163], v[44:47]
	v_mfma_f32_16x16x32_bf16 v[36:39], v[144:147], v[168:171], v[36:39]
	v_mfma_f32_16x16x32_bf16 v[28:31], v[152:155], v[168:171], v[28:31]
	v_mfma_f32_16x16x32_bf16 v[20:23], v[144:147], v[176:179], v[20:23]
	v_mfma_f32_16x16x32_bf16 v[12:15], v[152:155], v[176:179], v[12:15]
	v_mfma_f32_16x16x32_bf16 v[4:7], v[144:147], v[184:187], v[4:7]
	v_mfma_f32_16x16x32_bf16 v[0:3], v[152:155], v[184:187], v[0:3]
	v_mfma_f32_16x16x32_bf16 v[52:55], v[148:151], v[164:167], v[52:55]
	v_mfma_f32_16x16x32_bf16 v[44:47], v[156:159], v[164:167], v[44:47]
	v_mfma_f32_16x16x32_bf16 v[36:39], v[148:151], v[172:175], v[36:39]
	v_mfma_f32_16x16x32_bf16 v[28:31], v[156:159], v[172:175], v[28:31]
	v_mfma_f32_16x16x32_bf16 v[20:23], v[148:151], v[180:183], v[20:23]
	v_mfma_f32_16x16x32_bf16 v[12:15], v[156:159], v[180:183], v[12:15]
	v_mfma_f32_16x16x32_bf16 v[4:7], v[148:151], v[188:191], v[4:7]
	v_mfma_f32_16x16x32_bf16 v[0:3], v[156:159], v[188:191], v[0:3]
	s_barrier
	s_setprio 0
	s_add_i32 s94, 0, 0x18000
	s_add_i32 s95, 0, 0x1c000
	s_add_u32 s64, s64, 0x40000
	s_addc_u32 s65, s65, 0
	s_mov_b32 m0, s71
	v_lshl_add_u64 v[200:201], s[64:65], 0, v[206:207]
	global_load_lds_dwordx4 v[200:201], off
	v_lshl_add_u64 v[200:201], s[64:65], 0, v[210:211]
	s_mov_b32 m0, s72
	s_nop 0
	global_load_lds_dwordx4 v[200:201], off
	v_add_u32_e32 v140, s94, v234
	v_add_u32_e32 v156, s95, v234
	ds_read_b128 v[128:131], v140
	ds_read_b128 v[132:135], v140 offset:1024
	ds_read_b128 v[136:139], v140 offset:2048
	ds_read_b128 v[140:143], v140 offset:3072
	ds_read_b128 v[144:147], v156
	ds_read_b128 v[148:151], v156 offset:1024
	ds_read_b128 v[152:155], v156 offset:2048
	ds_read_b128 v[156:159], v156 offset:3072
	ds_read_b128 v[160:163], v237 offset:32768
	ds_read_b128 v[164:167], v237 offset:33792
	ds_read_b128 v[168:171], v237 offset:34816
	ds_read_b128 v[172:175], v237 offset:35840
	ds_read_b128 v[176:179], v237 offset:36864
	ds_read_b128 v[180:183], v237 offset:37888
	ds_read_b128 v[184:187], v237 offset:38912
	ds_read_b128 v[188:191], v237 offset:39936
	s_waitcnt vmcnt(8)
	s_waitcnt lgkmcnt(0)
	s_setprio 1
	s_barrier
	v_mfma_f32_16x16x32_bf16 v[124:127], v[128:131], v[160:163], v[124:127]
	v_mfma_f32_16x16x32_bf16 v[120:123], v[136:139], v[160:163], v[120:123]
	v_mfma_f32_16x16x32_bf16 v[116:119], v[128:131], v[168:171], v[116:119]
	v_mfma_f32_16x16x32_bf16 v[112:115], v[136:139], v[168:171], v[112:115]
	v_mfma_f32_16x16x32_bf16 v[108:111], v[128:131], v[176:179], v[108:111]
	v_mfma_f32_16x16x32_bf16 v[100:103], v[136:139], v[176:179], v[100:103]
	v_mfma_f32_16x16x32_bf16 v[92:95], v[128:131], v[184:187], v[92:95]
	v_mfma_f32_16x16x32_bf16 v[80:83], v[136:139], v[184:187], v[80:83]
	v_mfma_f32_16x16x32_bf16 v[124:127], v[132:135], v[164:167], v[124:127]
	v_mfma_f32_16x16x32_bf16 v[120:123], v[140:143], v[164:167], v[120:123]
	v_mfma_f32_16x16x32_bf16 v[116:119], v[132:135], v[172:175], v[116:119]
	v_mfma_f32_16x16x32_bf16 v[112:115], v[140:143], v[172:175], v[112:115]
	v_mfma_f32_16x16x32_bf16 v[108:111], v[132:135], v[180:183], v[108:111]
	v_mfma_f32_16x16x32_bf16 v[100:103], v[140:143], v[180:183], v[100:103]
	v_mfma_f32_16x16x32_bf16 v[92:95], v[132:135], v[188:191], v[92:95]
	v_mfma_f32_16x16x32_bf16 v[80:83], v[140:143], v[188:191], v[80:83]
	s_setprio 0
	s_setprio 1
	v_mfma_f32_16x16x32_bf16 v[104:107], v[144:147], v[160:163], v[104:107]
	v_mfma_f32_16x16x32_bf16 v[96:99], v[152:155], v[160:163], v[96:99]
	v_mfma_f32_16x16x32_bf16 v[88:91], v[144:147], v[168:171], v[88:91]
	v_mfma_f32_16x16x32_bf16 v[84:87], v[152:155], v[168:171], v[84:87]
	v_mfma_f32_16x16x32_bf16 v[76:79], v[144:147], v[176:179], v[76:79]
	v_mfma_f32_16x16x32_bf16 v[72:75], v[152:155], v[176:179], v[72:75]
	v_mfma_f32_16x16x32_bf16 v[68:71], v[144:147], v[184:187], v[68:71]
	v_mfma_f32_16x16x32_bf16 v[64:67], v[152:155], v[184:187], v[64:67]
	v_mfma_f32_16x16x32_bf16 v[104:107], v[148:151], v[164:167], v[104:107]
	v_mfma_f32_16x16x32_bf16 v[96:99], v[156:159], v[164:167], v[96:99]
	v_mfma_f32_16x16x32_bf16 v[88:91], v[148:151], v[172:175], v[88:91]
	v_mfma_f32_16x16x32_bf16 v[84:87], v[156:159], v[172:175], v[84:87]
	v_mfma_f32_16x16x32_bf16 v[76:79], v[148:151], v[180:183], v[76:79]
	v_mfma_f32_16x16x32_bf16 v[72:75], v[156:159], v[180:183], v[72:75]
	v_mfma_f32_16x16x32_bf16 v[68:71], v[148:151], v[188:191], v[68:71]
	v_mfma_f32_16x16x32_bf16 v[64:67], v[156:159], v[188:191], v[64:67]
	s_barrier
	s_setprio 0
	s_add_i32 s64, s94, s68
	v_lshl_add_u64 v[192:193], v[192:193], 0, s[14:15]
	s_mov_b32 m0, s64
	s_nop 0
	global_load_lds_dwordx4 v[192:193], off
	s_add_i32 m0, s64, 0x2000
	s_add_u32 s62, s62, 0x40080
	v_lshl_add_u64 v[192:193], v[194:195], 0, s[14:15]
	s_addc_u32 s63, s63, 0
	s_add_i32 s64, s95, s68
	global_load_lds_dwordx4 v[192:193], off
	v_lshl_add_u64 v[192:193], s[62:63], 0, v[208:209]
	s_mov_b32 m0, s64
	s_nop 0
	global_load_lds_dwordx4 v[192:193], off
	v_lshl_add_u64 v[192:193], s[62:63], 0, v[212:213]
	s_add_i32 m0, s64, 0x2000
	s_nop 0
	global_load_lds_dwordx4 v[192:193], off
	v_lshl_add_u64 v[192:193], v[196:197], 0, s[14:15]
	s_mov_b32 m0, s76
	s_nop 0
	global_load_lds_dwordx4 v[192:193], off
	v_lshl_add_u64 v[192:193], v[198:199], 0, s[14:15]
	s_mov_b32 m0, s77
	s_nop 0
	global_load_lds_dwordx4 v[192:193], off
	ds_read_b128 v[160:163], v237 offset:49152
	ds_read_b128 v[164:167], v237 offset:50176
	ds_read_b128 v[168:171], v237 offset:51200
	ds_read_b128 v[172:175], v237 offset:52224
	ds_read_b128 v[176:179], v237 offset:53248
	ds_read_b128 v[180:183], v237 offset:54272
	ds_read_b128 v[184:187], v237 offset:55296
	ds_read_b128 v[188:191], v237 offset:56320
	s_waitcnt vmcnt(8)
	s_waitcnt lgkmcnt(0)
	s_setprio 1
	s_barrier
	v_mfma_f32_16x16x32_bf16 v[60:63], v[128:131], v[160:163], v[60:63]
	v_mfma_f32_16x16x32_bf16 v[56:59], v[136:139], v[160:163], v[56:59]
	v_mfma_f32_16x16x32_bf16 v[48:51], v[128:131], v[168:171], v[48:51]
	v_mfma_f32_16x16x32_bf16 v[40:43], v[136:139], v[168:171], v[40:43]
	v_mfma_f32_16x16x32_bf16 v[32:35], v[128:131], v[176:179], v[32:35]
	v_mfma_f32_16x16x32_bf16 v[24:27], v[136:139], v[176:179], v[24:27]
	v_mfma_f32_16x16x32_bf16 v[16:19], v[128:131], v[184:187], v[16:19]
	v_mfma_f32_16x16x32_bf16 v[8:11], v[136:139], v[184:187], v[8:11]
	v_mfma_f32_16x16x32_bf16 v[60:63], v[132:135], v[164:167], v[60:63]
	v_mfma_f32_16x16x32_bf16 v[56:59], v[140:143], v[164:167], v[56:59]
	v_mfma_f32_16x16x32_bf16 v[48:51], v[132:135], v[172:175], v[48:51]
	v_mfma_f32_16x16x32_bf16 v[40:43], v[140:143], v[172:175], v[40:43]
	v_mfma_f32_16x16x32_bf16 v[32:35], v[132:135], v[180:183], v[32:35]
	v_mfma_f32_16x16x32_bf16 v[24:27], v[140:143], v[180:183], v[24:27]
	v_mfma_f32_16x16x32_bf16 v[16:19], v[132:135], v[188:191], v[16:19]
	v_mfma_f32_16x16x32_bf16 v[8:11], v[140:143], v[188:191], v[8:11]
	s_setprio 0
	s_setprio 1
	v_mfma_f32_16x16x32_bf16 v[52:55], v[144:147], v[160:163], v[52:55]
	v_mfma_f32_16x16x32_bf16 v[44:47], v[152:155], v[160:163], v[44:47]
	v_mfma_f32_16x16x32_bf16 v[36:39], v[144:147], v[168:171], v[36:39]
	v_mfma_f32_16x16x32_bf16 v[28:31], v[152:155], v[168:171], v[28:31]
	v_mfma_f32_16x16x32_bf16 v[20:23], v[144:147], v[176:179], v[20:23]
	v_mfma_f32_16x16x32_bf16 v[12:15], v[152:155], v[176:179], v[12:15]
	v_mfma_f32_16x16x32_bf16 v[4:7], v[144:147], v[184:187], v[4:7]
	v_mfma_f32_16x16x32_bf16 v[0:3], v[152:155], v[184:187], v[0:3]
	v_mfma_f32_16x16x32_bf16 v[52:55], v[148:151], v[164:167], v[52:55]
	v_mfma_f32_16x16x32_bf16 v[44:47], v[156:159], v[164:167], v[44:47]
	v_mfma_f32_16x16x32_bf16 v[36:39], v[148:151], v[172:175], v[36:39]
	v_mfma_f32_16x16x32_bf16 v[28:31], v[156:159], v[172:175], v[28:31]
	v_mfma_f32_16x16x32_bf16 v[20:23], v[148:151], v[180:183], v[20:23]
	v_mfma_f32_16x16x32_bf16 v[12:15], v[156:159], v[180:183], v[12:15]
	v_mfma_f32_16x16x32_bf16 v[4:7], v[148:151], v[188:191], v[4:7]
	v_mfma_f32_16x16x32_bf16 v[0:3], v[156:159], v[188:191], v[0:3]
	s_barrier
	s_setprio 0
	s_add_i32 s93, s93, 2
	s_add_u32 s48, s48, 0x100
	s_addc_u32 s49, s49, 0
	s_add_u32 s60, s60, 0x100
	s_addc_u32 s61, s61, 0
	s_cmp_gt_u32 s93, 13
	s_cbranch_scc0 .LBB0_723
	s_and_b64 vcc, exec, s[16:17]
	s_cbranch_vccz .LBB0_726
	s_barrier
	s_setprio 1

.LBB0_845:
	s_setprio 0
	s_waitcnt vmcnt(0)
	s_barrier
	s_load_dword s75, s[0:1], 0x160
	s_mov_b64 s[76:77], s[66:67]
	v_readlane_b32 s78, v255, 2

.Lph1109_w:
	s_nop 0
	s_nop 0
	s_nop 0
	s_waitcnt vmcnt(8)
	s_waitcnt lgkmcnt(0)
	s_setprio 1
	s_barrier
	v_mfma_f32_16x16x32_bf16 v[144:147], v[120:123], v[160:163], v[144:147]
	v_mfma_f32_16x16x32_bf16 v[136:139], v[128:131], v[160:163], v[136:139]
	v_mfma_f32_16x16x32_bf16 v[108:111], v[120:123], v[168:171], v[108:111]
	v_mfma_f32_16x16x32_bf16 v[104:107], v[128:131], v[168:171], v[104:107]
	v_mfma_f32_16x16x32_bf16 v[92:95], v[120:123], v[176:179], v[92:95]
	v_mfma_f32_16x16x32_bf16 v[88:91], v[128:131], v[176:179], v[88:91]
	v_mfma_f32_16x16x32_bf16 v[76:79], v[120:123], v[184:187], v[76:79]
	v_mfma_f32_16x16x32_bf16 v[72:75], v[128:131], v[184:187], v[72:75]
	v_mfma_f32_16x16x32_bf16 v[144:147], v[124:127], v[164:167], v[144:147]
	v_mfma_f32_16x16x32_bf16 v[136:139], v[132:135], v[164:167], v[136:139]
	v_mfma_f32_16x16x32_bf16 v[108:111], v[124:127], v[172:175], v[108:111]
	v_mfma_f32_16x16x32_bf16 v[104:107], v[132:135], v[172:175], v[104:107]
	v_mfma_f32_16x16x32_bf16 v[92:95], v[124:127], v[180:183], v[92:95]
	v_mfma_f32_16x16x32_bf16 v[88:91], v[132:135], v[180:183], v[88:91]
	v_mfma_f32_16x16x32_bf16 v[76:79], v[124:127], v[188:191], v[76:79]
	v_mfma_f32_16x16x32_bf16 v[72:75], v[132:135], v[188:191], v[72:75]
	s_setprio 0
	s_setprio 1
	v_mfma_f32_16x16x32_bf16 v[116:119], v[140:143], v[160:163], v[116:119]
	v_mfma_f32_16x16x32_bf16 v[112:115], v[152:155], v[160:163], v[112:115]
	v_mfma_f32_16x16x32_bf16 v[100:103], v[140:143], v[168:171], v[100:103]
	v_mfma_f32_16x16x32_bf16 v[96:99], v[152:155], v[168:171], v[96:99]
	v_mfma_f32_16x16x32_bf16 v[84:87], v[140:143], v[176:179], v[84:87]
	v_mfma_f32_16x16x32_bf16 v[80:83], v[152:155], v[176:179], v[80:83]
	v_mfma_f32_16x16x32_bf16 v[68:71], v[140:143], v[184:187], v[68:71]
	v_mfma_f32_16x16x32_bf16 v[64:67], v[152:155], v[184:187], v[64:67]
	v_mfma_f32_16x16x32_bf16 v[116:119], v[148:151], v[164:167], v[116:119]
	v_mfma_f32_16x16x32_bf16 v[112:115], v[156:159], v[164:167], v[112:115]
	v_mfma_f32_16x16x32_bf16 v[100:103], v[148:151], v[172:175], v[100:103]
	v_mfma_f32_16x16x32_bf16 v[96:99], v[156:159], v[172:175], v[96:99]
	v_mfma_f32_16x16x32_bf16 v[84:87], v[148:151], v[180:183], v[84:87]
	v_mfma_f32_16x16x32_bf16 v[80:83], v[156:159], v[180:183], v[80:83]
	v_mfma_f32_16x16x32_bf16 v[68:71], v[148:151], v[188:191], v[68:71]
	v_mfma_f32_16x16x32_bf16 v[64:67], v[156:159], v[188:191], v[64:67]
	s_barrier
	s_setprio 0
	s_add_i32 s65, s51, s37
	v_lshl_add_u64 v[206:207], s[30:31], 0, v[194:195]
	s_mov_b32 m0, s65
	s_nop 0
	global_load_lds_dwordx4 v[206:207], off
	s_add_i32 m0, s65, 0x2000
	s_add_u32 s66, s30, 0x40000
	v_lshl_add_u64 v[208:209], s[30:31], 0, v[198:199]
	s_addc_u32 s67, s31, 0
	s_add_i32 s65, s60, s37
	global_load_lds_dwordx4 v[208:209], off
	v_lshl_add_u64 v[210:211], s[66:67], 0, v[194:195]
	s_mov_b32 m0, s65
	v_lshl_add_u64 v[212:213], s[34:35], 0, v[196:197]
	global_load_lds_dwordx4 v[210:211], off
	v_lshl_add_u64 v[210:211], s[66:67], 0, v[198:199]
	s_add_i32 m0, s65, 0x2000
	s_nop 0
	global_load_lds_dwordx4 v[210:211], off
	v_lshl_add_u64 v[210:211], s[34:35], 0, v[192:193]
	s_mov_b32 m0, s27
	s_nop 0
	global_load_lds_dwordx4 v[210:211], off
	s_mov_b32 m0, s38
	s_nop 0
	global_load_lds_dwordx4 v[212:213], off
	ds_read_b128 v[160:163], v248 offset:16384
	ds_read_b128 v[164:167], v248 offset:17408
	ds_read_b128 v[168:171], v248 offset:18432
	ds_read_b128 v[172:175], v248 offset:19456
	ds_read_b128 v[176:179], v248 offset:20480
	ds_read_b128 v[180:183], v248 offset:21504
	ds_read_b128 v[184:187], v248 offset:22528
	ds_read_b128 v[188:191], v248 offset:23552
	s_nop 0
	s_waitcnt vmcnt(8)
	s_waitcnt lgkmcnt(0)
	s_setprio 1
	s_barrier
	v_mfma_f32_16x16x32_bf16 v[60:63], v[120:123], v[160:163], v[60:63]
	v_mfma_f32_16x16x32_bf16 v[56:59], v[128:131], v[160:163], v[56:59]
	v_mfma_f32_16x16x32_bf16 v[44:47], v[120:123], v[168:171], v[44:47]
	v_mfma_f32_16x16x32_bf16 v[40:43], v[128:131], v[168:171], v[40:43]
	v_mfma_f32_16x16x32_bf16 v[28:31], v[120:123], v[176:179], v[28:31]
	v_mfma_f32_16x16x32_bf16 v[24:27], v[128:131], v[176:179], v[24:27]
	v_mfma_f32_16x16x32_bf16 v[12:15], v[120:123], v[184:187], v[12:15]
	v_mfma_f32_16x16x32_bf16 v[8:11], v[128:131], v[184:187], v[8:11]
	v_mfma_f32_16x16x32_bf16 v[60:63], v[124:127], v[164:167], v[60:63]
	v_mfma_f32_16x16x32_bf16 v[56:59], v[132:135], v[164:167], v[56:59]
	v_mfma_f32_16x16x32_bf16 v[44:47], v[124:127], v[172:175], v[44:47]
	v_mfma_f32_16x16x32_bf16 v[40:43], v[132:135], v[172:175], v[40:43]
	v_mfma_f32_16x16x32_bf16 v[28:31], v[124:127], v[180:183], v[28:31]
	v_mfma_f32_16x16x32_bf16 v[24:27], v[132:135], v[180:183], v[24:27]
	v_mfma_f32_16x16x32_bf16 v[12:15], v[124:127], v[188:191], v[12:15]
	v_mfma_f32_16x16x32_bf16 v[8:11], v[132:135], v[188:191], v[8:11]
	s_setprio 0
	s_setprio 1
	v_mfma_f32_16x16x32_bf16 v[52:55], v[140:143], v[160:163], v[52:55]
	v_mfma_f32_16x16x32_bf16 v[48:51], v[152:155], v[160:163], v[48:51]
	v_mfma_f32_16x16x32_bf16 v[36:39], v[140:143], v[168:171], v[36:39]
	v_mfma_f32_16x16x32_bf16 v[32:35], v[152:155], v[168:171], v[32:35]
	v_mfma_f32_16x16x32_bf16 v[20:23], v[140:143], v[176:179], v[20:23]
	v_mfma_f32_16x16x32_bf16 v[16:19], v[152:155], v[176:179], v[16:19]
	v_mfma_f32_16x16x32_bf16 v[4:7], v[140:143], v[184:187], v[4:7]
	v_mfma_f32_16x16x32_bf16 v[0:3], v[152:155], v[184:187], v[0:3]
	v_mfma_f32_16x16x32_bf16 v[52:55], v[148:151], v[164:167], v[52:55]
	v_mfma_f32_16x16x32_bf16 v[48:51], v[156:159], v[164:167], v[48:51]
	v_mfma_f32_16x16x32_bf16 v[36:39], v[148:151], v[172:175], v[36:39]
	v_mfma_f32_16x16x32_bf16 v[32:35], v[156:159], v[172:175], v[32:35]
	v_mfma_f32_16x16x32_bf16 v[20:23], v[148:151], v[180:183], v[20:23]
	v_mfma_f32_16x16x32_bf16 v[16:19], v[156:159], v[180:183], v[16:19]
	v_mfma_f32_16x16x32_bf16 v[4:7], v[148:151], v[188:191], v[4:7]
	v_mfma_f32_16x16x32_bf16 v[0:3], v[156:159], v[188:191], v[0:3]
	s_barrier
	s_setprio 0
	s_add_i32 s65, 0, 0x18000
	s_add_i32 s66, 0, 0x1c000
	s_add_u32 s34, s34, 0x40000
	s_addc_u32 s35, s35, 0
	s_mov_b32 m0, s39
	v_lshl_add_u64 v[214:215], s[34:35], 0, v[192:193]
	global_load_lds_dwordx4 v[214:215], off
	v_lshl_add_u64 v[214:215], s[34:35], 0, v[196:197]
	s_mov_b32 m0, s40
	s_nop 0
	global_load_lds_dwordx4 v[214:215], off
	v_add_u32_e32 v132, s65, v245
	v_add_u32_e32 v156, s66, v245
	ds_read_b128 v[120:123], v132
	ds_read_b128 v[124:127], v132 offset:1024
	ds_read_b128 v[128:131], v132 offset:2048
	ds_read_b128 v[132:135], v132 offset:3072
	ds_read_b128 v[140:143], v156
	ds_read_b128 v[148:151], v156 offset:1024
	ds_read_b128 v[152:155], v156 offset:2048
	ds_read_b128 v[156:159], v156 offset:3072
	ds_read_b128 v[160:163], v248 offset:32768
	ds_read_b128 v[164:167], v248 offset:33792
	ds_read_b128 v[168:171], v248 offset:34816
	ds_read_b128 v[172:175], v248 offset:35840
	ds_read_b128 v[176:179], v248 offset:36864
	ds_read_b128 v[180:183], v248 offset:37888
	ds_read_b128 v[184:187], v248 offset:38912
	ds_read_b128 v[188:191], v248 offset:39936
	s_waitcnt vmcnt(8)
	s_waitcnt lgkmcnt(0)
	s_setprio 1
	s_barrier
	v_mfma_f32_16x16x32_bf16 v[144:147], v[120:123], v[160:163], v[144:147]
	v_mfma_f32_16x16x32_bf16 v[136:139], v[128:131], v[160:163], v[136:139]
	v_mfma_f32_16x16x32_bf16 v[108:111], v[120:123], v[168:171], v[108:111]
	v_mfma_f32_16x16x32_bf16 v[104:107], v[128:131], v[168:171], v[104:107]
	v_mfma_f32_16x16x32_bf16 v[92:95], v[120:123], v[176:179], v[92:95]
	v_mfma_f32_16x16x32_bf16 v[88:91], v[128:131], v[176:179], v[88:91]
	v_mfma_f32_16x16x32_bf16 v[76:79], v[120:123], v[184:187], v[76:79]
	v_mfma_f32_16x16x32_bf16 v[72:75], v[128:131], v[184:187], v[72:75]
	v_mfma_f32_16x16x32_bf16 v[144:147], v[124:127], v[164:167], v[144:147]
	v_mfma_f32_16x16x32_bf16 v[136:139], v[132:135], v[164:167], v[136:139]
	v_mfma_f32_16x16x32_bf16 v[108:111], v[124:127], v[172:175], v[108:111]
	v_mfma_f32_16x16x32_bf16 v[104:107], v[132:135], v[172:175], v[104:107]
	v_mfma_f32_16x16x32_bf16 v[92:95], v[124:127], v[180:183], v[92:95]
	v_mfma_f32_16x16x32_bf16 v[88:91], v[132:135], v[180:183], v[88:91]
	v_mfma_f32_16x16x32_bf16 v[76:79], v[124:127], v[188:191], v[76:79]
	v_mfma_f32_16x16x32_bf16 v[72:75], v[132:135], v[188:191], v[72:75]
	s_setprio 0
	s_setprio 1
	v_mfma_f32_16x16x32_bf16 v[116:119], v[140:143], v[160:163], v[116:119]
	v_mfma_f32_16x16x32_bf16 v[112:115], v[152:155], v[160:163], v[112:115]
	v_mfma_f32_16x16x32_bf16 v[100:103], v[140:143], v[168:171], v[100:103]
	v_mfma_f32_16x16x32_bf16 v[96:99], v[152:155], v[168:171], v[96:99]
	v_mfma_f32_16x16x32_bf16 v[84:87], v[140:143], v[176:179], v[84:87]
	v_mfma_f32_16x16x32_bf16 v[80:83], v[152:155], v[176:179], v[80:83]
	v_mfma_f32_16x16x32_bf16 v[68:71], v[140:143], v[184:187], v[68:71]
	v_mfma_f32_16x16x32_bf16 v[64:67], v[152:155], v[184:187], v[64:67]
	v_mfma_f32_16x16x32_bf16 v[116:119], v[148:151], v[164:167], v[116:119]
	v_mfma_f32_16x16x32_bf16 v[112:115], v[156:159], v[164:167], v[112:115]
	v_mfma_f32_16x16x32_bf16 v[100:103], v[148:151], v[172:175], v[100:103]
	v_mfma_f32_16x16x32_bf16 v[96:99], v[156:159], v[172:175], v[96:99]
	v_mfma_f32_16x16x32_bf16 v[84:87], v[148:151], v[180:183], v[84:87]
	v_mfma_f32_16x16x32_bf16 v[80:83], v[156:159], v[180:183], v[80:83]
	v_mfma_f32_16x16x32_bf16 v[68:71], v[148:151], v[188:191], v[68:71]
	v_mfma_f32_16x16x32_bf16 v[64:67], v[156:159], v[188:191], v[64:67]
	s_barrier
	s_setprio 0
	s_add_i32 s34, s65, s37
	v_lshl_add_u64 v[206:207], v[206:207], 0, s[12:13]
	s_mov_b32 m0, s34
	s_nop 0
	global_load_lds_dwordx4 v[206:207], off
	s_add_i32 m0, s34, 0x2000
	s_add_u32 s30, s30, 0x40080
	v_lshl_add_u64 v[206:207], v[208:209], 0, s[12:13]
	s_addc_u32 s31, s31, 0
	s_add_i32 s34, s66, s37
	global_load_lds_dwordx4 v[206:207], off
	v_lshl_add_u64 v[206:207], s[30:31], 0, v[194:195]
	s_mov_b32 m0, s34
	s_nop 0
	global_load_lds_dwordx4 v[206:207], off
	v_lshl_add_u64 v[206:207], s[30:31], 0, v[198:199]
	s_add_i32 m0, s34, 0x2000
	s_nop 0
	global_load_lds_dwordx4 v[206:207], off
	v_lshl_add_u64 v[206:207], v[210:211], 0, s[12:13]
	s_mov_b32 m0, s46
	s_nop 0
	global_load_lds_dwordx4 v[206:207], off
	v_lshl_add_u64 v[206:207], v[212:213], 0, s[12:13]
	s_mov_b32 m0, s47
	s_nop 0
	global_load_lds_dwordx4 v[206:207], off
	ds_read_b128 v[160:163], v248 offset:49152
	ds_read_b128 v[164:167], v248 offset:50176
	ds_read_b128 v[168:171], v248 offset:51200
	ds_read_b128 v[172:175], v248 offset:52224
	ds_read_b128 v[176:179], v248 offset:53248
	ds_read_b128 v[180:183], v248 offset:54272
	ds_read_b128 v[184:187], v248 offset:55296
	ds_read_b128 v[188:191], v248 offset:56320
	s_waitcnt vmcnt(8)
	s_waitcnt lgkmcnt(0)
	s_setprio 1
	s_barrier
	v_mfma_f32_16x16x32_bf16 v[60:63], v[120:123], v[160:163], v[60:63]
	v_mfma_f32_16x16x32_bf16 v[56:59], v[128:131], v[160:163], v[56:59]
	v_mfma_f32_16x16x32_bf16 v[44:47], v[120:123], v[168:171], v[44:47]
	v_mfma_f32_16x16x32_bf16 v[40:43], v[128:131], v[168:171], v[40:43]
	v_mfma_f32_16x16x32_bf16 v[28:31], v[120:123], v[176:179], v[28:31]
	v_mfma_f32_16x16x32_bf16 v[24:27], v[128:131], v[176:179], v[24:27]
	v_mfma_f32_16x16x32_bf16 v[12:15], v[120:123], v[184:187], v[12:15]
	v_mfma_f32_16x16x32_bf16 v[8:11], v[128:131], v[184:187], v[8:11]
	v_mfma_f32_16x16x32_bf16 v[60:63], v[124:127], v[164:167], v[60:63]
	v_mfma_f32_16x16x32_bf16 v[56:59], v[132:135], v[164:167], v[56:59]
	v_mfma_f32_16x16x32_bf16 v[44:47], v[124:127], v[172:175], v[44:47]
	v_mfma_f32_16x16x32_bf16 v[40:43], v[132:135], v[172:175], v[40:43]
	v_mfma_f32_16x16x32_bf16 v[28:31], v[124:127], v[180:183], v[28:31]
	v_mfma_f32_16x16x32_bf16 v[24:27], v[132:135], v[180:183], v[24:27]
	v_mfma_f32_16x16x32_bf16 v[12:15], v[124:127], v[188:191], v[12:15]
	v_mfma_f32_16x16x32_bf16 v[8:11], v[132:135], v[188:191], v[8:11]
	s_setprio 0
	s_setprio 1
	v_mfma_f32_16x16x32_bf16 v[52:55], v[140:143], v[160:163], v[52:55]
	v_mfma_f32_16x16x32_bf16 v[48:51], v[152:155], v[160:163], v[48:51]
	v_mfma_f32_16x16x32_bf16 v[36:39], v[140:143], v[168:171], v[36:39]
	v_mfma_f32_16x16x32_bf16 v[32:35], v[152:155], v[168:171], v[32:35]
	v_mfma_f32_16x16x32_bf16 v[20:23], v[140:143], v[176:179], v[20:23]
	v_mfma_f32_16x16x32_bf16 v[16:19], v[152:155], v[176:179], v[16:19]
	v_mfma_f32_16x16x32_bf16 v[4:7], v[140:143], v[184:187], v[4:7]
	v_mfma_f32_16x16x32_bf16 v[0:3], v[152:155], v[184:187], v[0:3]
	v_mfma_f32_16x16x32_bf16 v[52:55], v[148:151], v[164:167], v[52:55]
	v_mfma_f32_16x16x32_bf16 v[48:51], v[156:159], v[164:167], v[48:51]
	v_mfma_f32_16x16x32_bf16 v[36:39], v[148:151], v[172:175], v[36:39]
	v_mfma_f32_16x16x32_bf16 v[32:35], v[156:159], v[172:175], v[32:35]
	v_mfma_f32_16x16x32_bf16 v[20:23], v[148:151], v[180:183], v[20:23]
	v_mfma_f32_16x16x32_bf16 v[16:19], v[156:159], v[180:183], v[16:19]
	v_mfma_f32_16x16x32_bf16 v[4:7], v[148:151], v[188:191], v[4:7]
	v_mfma_f32_16x16x32_bf16 v[0:3], v[156:159], v[188:191], v[0:3]
	s_barrier
	s_setprio 0
	s_add_i32 s64, s64, 2
	s_add_u32 s28, s28, 0x100
	s_addc_u32 s29, s29, 0
	s_add_u32 s62, s62, 0x100
	s_addc_u32 s63, s63, 0
	s_cmp_gt_u32 s64, 13
	s_cbranch_scc0 .LBB0_1109
	s_and_b64 vcc, exec, s[14:15]
	s_cbranch_vccz .LBB0_1112
	s_barrier
	s_setprio 1

.Lph1193_w:
	s_nop 0
	s_waitcnt vmcnt(8)
	s_waitcnt lgkmcnt(0)
	s_setprio 1
	s_barrier
	v_mfma_f32_16x16x32_bf16 v[116:119], v[154:157], v[186:189], v[116:119]
	v_mfma_f32_16x16x32_bf16 v[112:115], v[162:165], v[186:189], v[112:115]
	v_mfma_f32_16x16x32_bf16 v[108:111], v[154:157], v[194:197], v[108:111]
	v_mfma_f32_16x16x32_bf16 v[100:103], v[162:165], v[194:197], v[100:103]
	v_mfma_f32_16x16x32_bf16 v[92:95], v[154:157], v[202:205], v[92:95]
	v_mfma_f32_16x16x32_bf16 v[84:87], v[162:165], v[202:205], v[84:87]
	v_mfma_f32_16x16x32_bf16 v[76:79], v[154:157], v[210:213], v[76:79]
	v_mfma_f32_16x16x32_bf16 v[68:71], v[162:165], v[210:213], v[68:71]
	v_mfma_f32_16x16x32_bf16 v[116:119], v[158:161], v[190:193], v[116:119]
	v_mfma_f32_16x16x32_bf16 v[112:115], v[166:169], v[190:193], v[112:115]
	v_mfma_f32_16x16x32_bf16 v[108:111], v[158:161], v[198:201], v[108:111]
	v_mfma_f32_16x16x32_bf16 v[100:103], v[166:169], v[198:201], v[100:103]
	v_mfma_f32_16x16x32_bf16 v[92:95], v[158:161], v[206:209], v[92:95]
	v_mfma_f32_16x16x32_bf16 v[84:87], v[166:169], v[206:209], v[84:87]
	v_mfma_f32_16x16x32_bf16 v[76:79], v[158:161], v[214:217], v[76:79]
	v_mfma_f32_16x16x32_bf16 v[68:71], v[166:169], v[214:217], v[68:71]
	s_setprio 0
	s_setprio 1
	v_mfma_f32_16x16x32_bf16 v[124:127], v[170:173], v[186:189], v[124:127]
	v_mfma_f32_16x16x32_bf16 v[120:123], v[178:181], v[186:189], v[120:123]
	v_mfma_f32_16x16x32_bf16 v[104:107], v[170:173], v[194:197], v[104:107]
	v_mfma_f32_16x16x32_bf16 v[96:99], v[178:181], v[194:197], v[96:99]
	v_mfma_f32_16x16x32_bf16 v[88:91], v[170:173], v[202:205], v[88:91]
	v_mfma_f32_16x16x32_bf16 v[80:83], v[178:181], v[202:205], v[80:83]
	v_mfma_f32_16x16x32_bf16 v[72:75], v[170:173], v[210:213], v[72:75]
	v_mfma_f32_16x16x32_bf16 v[64:67], v[178:181], v[210:213], v[64:67]
	v_mfma_f32_16x16x32_bf16 v[124:127], v[174:177], v[190:193], v[124:127]
	v_mfma_f32_16x16x32_bf16 v[120:123], v[182:185], v[190:193], v[120:123]
	v_mfma_f32_16x16x32_bf16 v[104:107], v[174:177], v[198:201], v[104:107]
	v_mfma_f32_16x16x32_bf16 v[96:99], v[182:185], v[198:201], v[96:99]
	v_mfma_f32_16x16x32_bf16 v[88:91], v[174:177], v[206:209], v[88:91]
	v_mfma_f32_16x16x32_bf16 v[80:83], v[182:185], v[206:209], v[80:83]
	v_mfma_f32_16x16x32_bf16 v[72:75], v[174:177], v[214:217], v[72:75]
	v_mfma_f32_16x16x32_bf16 v[64:67], v[182:185], v[214:217], v[64:67]
	s_barrier
	s_setprio 0
	s_add_i32 s63, s47, s5
	v_lshl_add_u64 v[144:145], s[30:31], 0, v[132:133]
	s_mov_b32 m0, s63
	s_nop 0
	global_load_lds_dwordx4 v[144:145], off
	s_add_i32 m0, s63, 0x2000
	s_add_u32 s64, s30, 0x40000
	v_lshl_add_u64 v[218:219], s[30:31], 0, v[128:129]
	s_addc_u32 s65, s31, 0
	s_add_i32 s63, s48, s5
	global_load_lds_dwordx4 v[218:219], off
	v_lshl_add_u64 v[220:221], s[64:65], 0, v[132:133]
	s_mov_b32 m0, s63
	v_lshl_add_u64 v[222:223], s[34:35], 0, v[130:131]
	global_load_lds_dwordx4 v[220:221], off
	v_lshl_add_u64 v[220:221], s[64:65], 0, v[128:129]
	s_add_i32 m0, s63, 0x2000
	s_nop 0
	global_load_lds_dwordx4 v[220:221], off
	v_lshl_add_u64 v[220:221], s[34:35], 0, v[134:135]
	s_mov_b32 m0, s25
	s_nop 0
	global_load_lds_dwordx4 v[220:221], off
	s_mov_b32 m0, s27
	s_nop 0
	global_load_lds_dwordx4 v[222:223], off
	ds_read_b128 v[186:189], v151 offset:16384
	ds_read_b128 v[190:193], v151 offset:17408
	ds_read_b128 v[194:197], v151 offset:18432
	ds_read_b128 v[198:201], v151 offset:19456
	ds_read_b128 v[202:205], v151 offset:20480
	ds_read_b128 v[206:209], v151 offset:21504
	ds_read_b128 v[210:213], v151 offset:22528
	ds_read_b128 v[214:217], v151 offset:23552
	s_nop 0
	s_waitcnt vmcnt(8)
	s_waitcnt lgkmcnt(0)
	s_setprio 1
	s_barrier
	v_mfma_f32_16x16x32_bf16 v[60:63], v[154:157], v[186:189], v[60:63]
	v_mfma_f32_16x16x32_bf16 v[52:55], v[162:165], v[186:189], v[52:55]
	v_mfma_f32_16x16x32_bf16 v[44:47], v[154:157], v[194:197], v[44:47]
	v_mfma_f32_16x16x32_bf16 v[36:39], v[162:165], v[194:197], v[36:39]
	v_mfma_f32_16x16x32_bf16 v[28:31], v[154:157], v[202:205], v[28:31]
	v_mfma_f32_16x16x32_bf16 v[20:23], v[162:165], v[202:205], v[20:23]
	v_mfma_f32_16x16x32_bf16 v[12:15], v[154:157], v[210:213], v[12:15]
	v_mfma_f32_16x16x32_bf16 v[4:7], v[162:165], v[210:213], v[4:7]
	v_mfma_f32_16x16x32_bf16 v[60:63], v[158:161], v[190:193], v[60:63]
	v_mfma_f32_16x16x32_bf16 v[52:55], v[166:169], v[190:193], v[52:55]
	v_mfma_f32_16x16x32_bf16 v[44:47], v[158:161], v[198:201], v[44:47]
	v_mfma_f32_16x16x32_bf16 v[36:39], v[166:169], v[198:201], v[36:39]
	v_mfma_f32_16x16x32_bf16 v[28:31], v[158:161], v[206:209], v[28:31]
	v_mfma_f32_16x16x32_bf16 v[20:23], v[166:169], v[206:209], v[20:23]
	v_mfma_f32_16x16x32_bf16 v[12:15], v[158:161], v[214:217], v[12:15]
	v_mfma_f32_16x16x32_bf16 v[4:7], v[166:169], v[214:217], v[4:7]
	s_setprio 0
	s_setprio 1
	v_mfma_f32_16x16x32_bf16 v[56:59], v[170:173], v[186:189], v[56:59]
	v_mfma_f32_16x16x32_bf16 v[48:51], v[178:181], v[186:189], v[48:51]
	v_mfma_f32_16x16x32_bf16 v[40:43], v[170:173], v[194:197], v[40:43]
	v_mfma_f32_16x16x32_bf16 v[32:35], v[178:181], v[194:197], v[32:35]
	v_mfma_f32_16x16x32_bf16 v[24:27], v[170:173], v[202:205], v[24:27]
	v_mfma_f32_16x16x32_bf16 v[16:19], v[178:181], v[202:205], v[16:19]
	v_mfma_f32_16x16x32_bf16 v[8:11], v[170:173], v[210:213], v[8:11]
	v_mfma_f32_16x16x32_bf16 v[0:3], v[178:181], v[210:213], v[0:3]
	v_mfma_f32_16x16x32_bf16 v[56:59], v[174:177], v[190:193], v[56:59]
	v_mfma_f32_16x16x32_bf16 v[48:51], v[182:185], v[190:193], v[48:51]
	v_mfma_f32_16x16x32_bf16 v[40:43], v[174:177], v[198:201], v[40:43]
	v_mfma_f32_16x16x32_bf16 v[32:35], v[182:185], v[198:201], v[32:35]
	v_mfma_f32_16x16x32_bf16 v[24:27], v[174:177], v[206:209], v[24:27]
	v_mfma_f32_16x16x32_bf16 v[16:19], v[182:185], v[206:209], v[16:19]
	v_mfma_f32_16x16x32_bf16 v[8:11], v[174:177], v[214:217], v[8:11]
	v_mfma_f32_16x16x32_bf16 v[0:3], v[182:185], v[214:217], v[0:3]
	s_barrier
	s_setprio 0
	s_add_i32 s63, 0, 0x18000
	s_add_i32 s64, 0, 0x1c000
	s_add_u32 s34, s34, 0x40000
	s_addc_u32 s35, s35, 0
	s_mov_b32 m0, s38
	v_lshl_add_u64 v[224:225], s[34:35], 0, v[134:135]
	global_load_lds_dwordx4 v[224:225], off
	v_lshl_add_u64 v[224:225], s[34:35], 0, v[130:131]
	s_mov_b32 m0, s39
	s_nop 0
	global_load_lds_dwordx4 v[224:225], off
	v_add_u32_e32 v153, s63, v147
	ds_read_b128 v[154:157], v153
	ds_read_b128 v[158:161], v153 offset:1024
	ds_read_b128 v[162:165], v153 offset:2048
	ds_read_b128 v[166:169], v153 offset:3072
	v_add_u32_e32 v153, s64, v147
	ds_read_b128 v[170:173], v153
	ds_read_b128 v[174:177], v153 offset:1024
	ds_read_b128 v[178:181], v153 offset:2048
	ds_read_b128 v[182:185], v153 offset:3072
	ds_read_b128 v[186:189], v151 offset:32768
	ds_read_b128 v[190:193], v151 offset:33792
	ds_read_b128 v[194:197], v151 offset:34816
	ds_read_b128 v[198:201], v151 offset:35840
	ds_read_b128 v[202:205], v151 offset:36864
	ds_read_b128 v[206:209], v151 offset:37888
	ds_read_b128 v[210:213], v151 offset:38912
	ds_read_b128 v[214:217], v151 offset:39936
	s_waitcnt vmcnt(8)
	s_waitcnt lgkmcnt(0)
	s_setprio 1
	s_barrier
	v_mfma_f32_16x16x32_bf16 v[116:119], v[154:157], v[186:189], v[116:119]
	v_mfma_f32_16x16x32_bf16 v[112:115], v[162:165], v[186:189], v[112:115]
	v_mfma_f32_16x16x32_bf16 v[108:111], v[154:157], v[194:197], v[108:111]
	v_mfma_f32_16x16x32_bf16 v[100:103], v[162:165], v[194:197], v[100:103]
	v_mfma_f32_16x16x32_bf16 v[92:95], v[154:157], v[202:205], v[92:95]
	v_mfma_f32_16x16x32_bf16 v[84:87], v[162:165], v[202:205], v[84:87]
	v_mfma_f32_16x16x32_bf16 v[76:79], v[154:157], v[210:213], v[76:79]
	v_mfma_f32_16x16x32_bf16 v[68:71], v[162:165], v[210:213], v[68:71]
	v_mfma_f32_16x16x32_bf16 v[116:119], v[158:161], v[190:193], v[116:119]
	v_mfma_f32_16x16x32_bf16 v[112:115], v[166:169], v[190:193], v[112:115]
	v_mfma_f32_16x16x32_bf16 v[108:111], v[158:161], v[198:201], v[108:111]
	v_mfma_f32_16x16x32_bf16 v[100:103], v[166:169], v[198:201], v[100:103]
	v_mfma_f32_16x16x32_bf16 v[92:95], v[158:161], v[206:209], v[92:95]
	v_mfma_f32_16x16x32_bf16 v[84:87], v[166:169], v[206:209], v[84:87]
	v_mfma_f32_16x16x32_bf16 v[76:79], v[158:161], v[214:217], v[76:79]
	v_mfma_f32_16x16x32_bf16 v[68:71], v[166:169], v[214:217], v[68:71]
	s_setprio 0
	s_setprio 1
	v_mfma_f32_16x16x32_bf16 v[124:127], v[170:173], v[186:189], v[124:127]
	v_mfma_f32_16x16x32_bf16 v[120:123], v[178:181], v[186:189], v[120:123]
	v_mfma_f32_16x16x32_bf16 v[104:107], v[170:173], v[194:197], v[104:107]
	v_mfma_f32_16x16x32_bf16 v[96:99], v[178:181], v[194:197], v[96:99]
	v_mfma_f32_16x16x32_bf16 v[88:91], v[170:173], v[202:205], v[88:91]
	v_mfma_f32_16x16x32_bf16 v[80:83], v[178:181], v[202:205], v[80:83]
	v_mfma_f32_16x16x32_bf16 v[72:75], v[170:173], v[210:213], v[72:75]
	v_mfma_f32_16x16x32_bf16 v[64:67], v[178:181], v[210:213], v[64:67]
	v_mfma_f32_16x16x32_bf16 v[124:127], v[174:177], v[190:193], v[124:127]
	v_mfma_f32_16x16x32_bf16 v[120:123], v[182:185], v[190:193], v[120:123]
	v_mfma_f32_16x16x32_bf16 v[104:107], v[174:177], v[198:201], v[104:107]
	v_mfma_f32_16x16x32_bf16 v[96:99], v[182:185], v[198:201], v[96:99]
	v_mfma_f32_16x16x32_bf16 v[88:91], v[174:177], v[206:209], v[88:91]
	v_mfma_f32_16x16x32_bf16 v[80:83], v[182:185], v[206:209], v[80:83]
	v_mfma_f32_16x16x32_bf16 v[72:75], v[174:177], v[214:217], v[72:75]
	v_mfma_f32_16x16x32_bf16 v[64:67], v[182:185], v[214:217], v[64:67]
	s_barrier
	s_setprio 0
	s_add_i32 s34, s63, s5
	v_lshl_add_u64 v[144:145], v[144:145], 0, s[12:13]
	s_mov_b32 m0, s34
	s_nop 0
	global_load_lds_dwordx4 v[144:145], off
	s_add_i32 m0, s34, 0x2000
	s_add_u32 s30, s30, 0x40080
	v_lshl_add_u64 v[144:145], v[218:219], 0, s[12:13]
	s_addc_u32 s31, s31, 0
	s_add_i32 s34, s64, s5
	global_load_lds_dwordx4 v[144:145], off
	v_lshl_add_u64 v[144:145], s[30:31], 0, v[132:133]
	s_mov_b32 m0, s34
	s_nop 0
	global_load_lds_dwordx4 v[144:145], off
	v_lshl_add_u64 v[144:145], s[30:31], 0, v[128:129]
	s_add_i32 m0, s34, 0x2000
	s_nop 0
	global_load_lds_dwordx4 v[144:145], off
	v_lshl_add_u64 v[144:145], v[220:221], 0, s[12:13]
	s_mov_b32 m0, s41
	s_nop 0
	global_load_lds_dwordx4 v[144:145], off
	v_lshl_add_u64 v[144:145], v[222:223], 0, s[12:13]
	s_mov_b32 m0, s42
	s_nop 0
	global_load_lds_dwordx4 v[144:145], off
	ds_read_b128 v[186:189], v151 offset:49152
	ds_read_b128 v[190:193], v151 offset:50176
	ds_read_b128 v[194:197], v151 offset:51200
	ds_read_b128 v[198:201], v151 offset:52224
	ds_read_b128 v[202:205], v151 offset:53248
	ds_read_b128 v[206:209], v151 offset:54272
	ds_read_b128 v[210:213], v151 offset:55296
	ds_read_b128 v[214:217], v151 offset:56320
	s_waitcnt vmcnt(8)
	s_waitcnt lgkmcnt(0)
	s_setprio 1
	s_barrier
	v_mfma_f32_16x16x32_bf16 v[60:63], v[154:157], v[186:189], v[60:63]
	v_mfma_f32_16x16x32_bf16 v[52:55], v[162:165], v[186:189], v[52:55]
	v_mfma_f32_16x16x32_bf16 v[44:47], v[154:157], v[194:197], v[44:47]
	v_mfma_f32_16x16x32_bf16 v[36:39], v[162:165], v[194:197], v[36:39]
	v_mfma_f32_16x16x32_bf16 v[28:31], v[154:157], v[202:205], v[28:31]
	v_mfma_f32_16x16x32_bf16 v[20:23], v[162:165], v[202:205], v[20:23]
	v_mfma_f32_16x16x32_bf16 v[12:15], v[154:157], v[210:213], v[12:15]
	v_mfma_f32_16x16x32_bf16 v[4:7], v[162:165], v[210:213], v[4:7]
	v_mfma_f32_16x16x32_bf16 v[60:63], v[158:161], v[190:193], v[60:63]
	v_mfma_f32_16x16x32_bf16 v[52:55], v[166:169], v[190:193], v[52:55]
	v_mfma_f32_16x16x32_bf16 v[44:47], v[158:161], v[198:201], v[44:47]
	v_mfma_f32_16x16x32_bf16 v[36:39], v[166:169], v[198:201], v[36:39]
	v_mfma_f32_16x16x32_bf16 v[28:31], v[158:161], v[206:209], v[28:31]
	v_mfma_f32_16x16x32_bf16 v[20:23], v[166:169], v[206:209], v[20:23]
	v_mfma_f32_16x16x32_bf16 v[12:15], v[158:161], v[214:217], v[12:15]
	v_mfma_f32_16x16x32_bf16 v[4:7], v[166:169], v[214:217], v[4:7]
	s_setprio 0
	s_setprio 1
	v_mfma_f32_16x16x32_bf16 v[56:59], v[170:173], v[186:189], v[56:59]
	v_mfma_f32_16x16x32_bf16 v[48:51], v[178:181], v[186:189], v[48:51]
	v_mfma_f32_16x16x32_bf16 v[40:43], v[170:173], v[194:197], v[40:43]
	v_mfma_f32_16x16x32_bf16 v[32:35], v[178:181], v[194:197], v[32:35]
	v_mfma_f32_16x16x32_bf16 v[24:27], v[170:173], v[202:205], v[24:27]
	v_mfma_f32_16x16x32_bf16 v[16:19], v[178:181], v[202:205], v[16:19]
	v_mfma_f32_16x16x32_bf16 v[8:11], v[170:173], v[210:213], v[8:11]
	v_mfma_f32_16x16x32_bf16 v[0:3], v[178:181], v[210:213], v[0:3]
	v_mfma_f32_16x16x32_bf16 v[56:59], v[174:177], v[190:193], v[56:59]
	v_mfma_f32_16x16x32_bf16 v[48:51], v[182:185], v[190:193], v[48:51]
	v_mfma_f32_16x16x32_bf16 v[40:43], v[174:177], v[198:201], v[40:43]
	v_mfma_f32_16x16x32_bf16 v[32:35], v[182:185], v[198:201], v[32:35]
	v_mfma_f32_16x16x32_bf16 v[24:27], v[174:177], v[206:209], v[24:27]
	v_mfma_f32_16x16x32_bf16 v[16:19], v[182:185], v[206:209], v[16:19]
	v_mfma_f32_16x16x32_bf16 v[8:11], v[174:177], v[214:217], v[8:11]
	v_mfma_f32_16x16x32_bf16 v[0:3], v[182:185], v[214:217], v[0:3]
	s_barrier
	s_setprio 0
	s_add_i32 s62, s62, 2
	s_add_u32 s28, s28, 0x100
	s_addc_u32 s29, s29, 0
	s_add_u32 s60, s60, 0x100
	s_addc_u32 s61, s61, 0
	s_cmp_gt_u32 s62, 13
	s_cbranch_scc0 .LBB0_1193
	s_and_b64 vcc, exec, s[14:15]
	s_cbranch_vccz .LBB0_1196
	s_barrier
	s_setprio 1

.Lph1273_w:
	s_nop 0
	s_nop 0
	s_waitcnt vmcnt(8)
	s_waitcnt lgkmcnt(0)
	s_setprio 1
	s_barrier
	v_mfma_f32_16x16x32_bf16 v[124:127], v[128:131], v[160:163], v[124:127]
	v_mfma_f32_16x16x32_bf16 v[120:123], v[136:139], v[160:163], v[120:123]
	v_mfma_f32_16x16x32_bf16 v[112:115], v[128:131], v[184:187], v[112:115]
	v_mfma_f32_16x16x32_bf16 v[104:107], v[136:139], v[184:187], v[104:107]
	v_mfma_f32_16x16x32_bf16 v[96:99], v[128:131], v[200:203], v[96:99]
	v_mfma_f32_16x16x32_bf16 v[88:91], v[136:139], v[200:203], v[88:91]
	v_mfma_f32_16x16x32_bf16 v[80:83], v[128:131], v[208:211], v[80:83]
	v_mfma_f32_16x16x32_bf16 v[72:75], v[136:139], v[208:211], v[72:75]
	v_mfma_f32_16x16x32_bf16 v[124:127], v[132:135], v[180:183], v[124:127]
	v_mfma_f32_16x16x32_bf16 v[120:123], v[140:143], v[180:183], v[120:123]
	v_mfma_f32_16x16x32_bf16 v[112:115], v[132:135], v[188:191], v[112:115]
	v_mfma_f32_16x16x32_bf16 v[104:107], v[140:143], v[188:191], v[104:107]
	v_mfma_f32_16x16x32_bf16 v[96:99], v[132:135], v[204:207], v[96:99]
	v_mfma_f32_16x16x32_bf16 v[88:91], v[140:143], v[204:207], v[88:91]
	v_mfma_f32_16x16x32_bf16 v[80:83], v[132:135], v[212:215], v[80:83]
	v_mfma_f32_16x16x32_bf16 v[72:75], v[140:143], v[212:215], v[72:75]
	s_setprio 0
	s_setprio 1
	v_mfma_f32_16x16x32_bf16 v[116:119], v[144:147], v[160:163], v[116:119]
	v_mfma_f32_16x16x32_bf16 v[108:111], v[152:155], v[160:163], v[108:111]
	v_mfma_f32_16x16x32_bf16 v[100:103], v[144:147], v[184:187], v[100:103]
	v_mfma_f32_16x16x32_bf16 v[92:95], v[152:155], v[184:187], v[92:95]
	v_mfma_f32_16x16x32_bf16 v[84:87], v[144:147], v[200:203], v[84:87]
	v_mfma_f32_16x16x32_bf16 v[76:79], v[152:155], v[200:203], v[76:79]
	v_mfma_f32_16x16x32_bf16 v[68:71], v[144:147], v[208:211], v[68:71]
	v_mfma_f32_16x16x32_bf16 v[64:67], v[152:155], v[208:211], v[64:67]
	v_mfma_f32_16x16x32_bf16 v[116:119], v[148:151], v[180:183], v[116:119]
	v_mfma_f32_16x16x32_bf16 v[108:111], v[156:159], v[180:183], v[108:111]
	v_mfma_f32_16x16x32_bf16 v[100:103], v[148:151], v[188:191], v[100:103]
	v_mfma_f32_16x16x32_bf16 v[92:95], v[156:159], v[188:191], v[92:95]
	v_mfma_f32_16x16x32_bf16 v[84:87], v[148:151], v[204:207], v[84:87]
	v_mfma_f32_16x16x32_bf16 v[76:79], v[156:159], v[204:207], v[76:79]
	v_mfma_f32_16x16x32_bf16 v[68:71], v[148:151], v[212:215], v[68:71]
	v_mfma_f32_16x16x32_bf16 v[64:67], v[156:159], v[212:215], v[64:67]
	s_barrier
	s_setprio 0
	s_add_i32 s16, s38, s25
	v_lshl_add_u64 v[192:193], s[20:21], 0, v[166:167]
	s_mov_b32 m0, s16
	s_nop 0
	global_load_lds_dwordx4 v[192:193], off
	s_add_i32 m0, s16, 0x2000
	s_add_u32 s16, s20, 0xb0000
	v_lshl_add_u64 v[216:217], s[20:21], 0, v[170:171]
	s_addc_u32 s17, s21, 0
	s_add_i32 s47, s39, s25
	global_load_lds_dwordx4 v[216:217], off
	v_lshl_add_u64 v[218:219], s[16:17], 0, v[166:167]
	s_mov_b32 m0, s47
	v_lshl_add_u64 v[220:221], s[22:23], 0, v[168:169]
	global_load_lds_dwordx4 v[218:219], off
	v_lshl_add_u64 v[218:219], s[16:17], 0, v[170:171]
	s_add_i32 m0, s47, 0x2000
	s_nop 0
	global_load_lds_dwordx4 v[218:219], off
	v_lshl_add_u64 v[218:219], s[22:23], 0, v[164:165]
	s_mov_b32 m0, s26
	s_nop 0
	global_load_lds_dwordx4 v[218:219], off
	s_mov_b32 m0, s27
	s_nop 0
	global_load_lds_dwordx4 v[220:221], off
	ds_read_b128 v[160:163], v199 offset:16384
	ds_read_b128 v[180:183], v199 offset:17408
	ds_read_b128 v[184:187], v199 offset:18432
	ds_read_b128 v[188:191], v199 offset:19456
	ds_read_b128 v[200:203], v199 offset:20480
	ds_read_b128 v[204:207], v199 offset:21504
	ds_read_b128 v[208:211], v199 offset:22528
	ds_read_b128 v[212:215], v199 offset:23552
	s_nop 0
	s_waitcnt vmcnt(8)
	s_waitcnt lgkmcnt(0)
	s_setprio 1
	s_barrier
	v_mfma_f32_16x16x32_bf16 v[60:63], v[128:131], v[160:163], v[60:63]
	v_mfma_f32_16x16x32_bf16 v[56:59], v[136:139], v[160:163], v[56:59]
	v_mfma_f32_16x16x32_bf16 v[48:51], v[128:131], v[184:187], v[48:51]
	v_mfma_f32_16x16x32_bf16 v[40:43], v[136:139], v[184:187], v[40:43]
	v_mfma_f32_16x16x32_bf16 v[32:35], v[128:131], v[200:203], v[32:35]
	v_mfma_f32_16x16x32_bf16 v[24:27], v[136:139], v[200:203], v[24:27]
	v_mfma_f32_16x16x32_bf16 v[16:19], v[128:131], v[208:211], v[16:19]
	v_mfma_f32_16x16x32_bf16 v[8:11], v[136:139], v[208:211], v[8:11]
	v_mfma_f32_16x16x32_bf16 v[60:63], v[132:135], v[180:183], v[60:63]
	v_mfma_f32_16x16x32_bf16 v[56:59], v[140:143], v[180:183], v[56:59]
	v_mfma_f32_16x16x32_bf16 v[48:51], v[132:135], v[188:191], v[48:51]
	v_mfma_f32_16x16x32_bf16 v[40:43], v[140:143], v[188:191], v[40:43]
	v_mfma_f32_16x16x32_bf16 v[32:35], v[132:135], v[204:207], v[32:35]
	v_mfma_f32_16x16x32_bf16 v[24:27], v[140:143], v[204:207], v[24:27]
	v_mfma_f32_16x16x32_bf16 v[16:19], v[132:135], v[212:215], v[16:19]
	v_mfma_f32_16x16x32_bf16 v[8:11], v[140:143], v[212:215], v[8:11]
	s_setprio 0
	s_setprio 1
	v_mfma_f32_16x16x32_bf16 v[52:55], v[144:147], v[160:163], v[52:55]
	v_mfma_f32_16x16x32_bf16 v[44:47], v[152:155], v[160:163], v[44:47]
	v_mfma_f32_16x16x32_bf16 v[36:39], v[144:147], v[184:187], v[36:39]
	v_mfma_f32_16x16x32_bf16 v[28:31], v[152:155], v[184:187], v[28:31]
	v_mfma_f32_16x16x32_bf16 v[20:23], v[144:147], v[200:203], v[20:23]
	v_mfma_f32_16x16x32_bf16 v[12:15], v[152:155], v[200:203], v[12:15]
	v_mfma_f32_16x16x32_bf16 v[4:7], v[144:147], v[208:211], v[4:7]
	v_mfma_f32_16x16x32_bf16 v[0:3], v[152:155], v[208:211], v[0:3]
	v_mfma_f32_16x16x32_bf16 v[52:55], v[148:151], v[180:183], v[52:55]
	v_mfma_f32_16x16x32_bf16 v[44:47], v[156:159], v[180:183], v[44:47]
	v_mfma_f32_16x16x32_bf16 v[36:39], v[148:151], v[188:191], v[36:39]
	v_mfma_f32_16x16x32_bf16 v[28:31], v[156:159], v[188:191], v[28:31]
	v_mfma_f32_16x16x32_bf16 v[20:23], v[148:151], v[204:207], v[20:23]
	v_mfma_f32_16x16x32_bf16 v[12:15], v[156:159], v[204:207], v[12:15]
	v_mfma_f32_16x16x32_bf16 v[4:7], v[148:151], v[212:215], v[4:7]
	v_mfma_f32_16x16x32_bf16 v[0:3], v[156:159], v[212:215], v[0:3]
	s_barrier
	s_setprio 0
	s_add_i32 s47, 0, 0x18000
	s_add_i32 s48, 0, 0x1c000
	s_add_u32 s16, s22, 0xb0000
	s_addc_u32 s17, s23, 0
	s_mov_b32 m0, s28
	v_lshl_add_u64 v[222:223], s[16:17], 0, v[164:165]
	global_load_lds_dwordx4 v[222:223], off
	v_lshl_add_u64 v[222:223], s[16:17], 0, v[168:169]
	s_mov_b32 m0, s29
	s_nop 0
	global_load_lds_dwordx4 v[222:223], off
	v_add_u32_e32 v140, s47, v196
	v_add_u32_e32 v156, s48, v196
	ds_read_b128 v[128:131], v140
	ds_read_b128 v[132:135], v140 offset:1024
	ds_read_b128 v[136:139], v140 offset:2048
	ds_read_b128 v[140:143], v140 offset:3072
	ds_read_b128 v[144:147], v156
	ds_read_b128 v[148:151], v156 offset:1024
	ds_read_b128 v[152:155], v156 offset:2048
	ds_read_b128 v[156:159], v156 offset:3072
	ds_read_b128 v[160:163], v199 offset:32768
	ds_read_b128 v[180:183], v199 offset:33792
	ds_read_b128 v[184:187], v199 offset:34816
	ds_read_b128 v[188:191], v199 offset:35840
	ds_read_b128 v[200:203], v199 offset:36864
	ds_read_b128 v[204:207], v199 offset:37888
	ds_read_b128 v[208:211], v199 offset:38912
	ds_read_b128 v[212:215], v199 offset:39936
	s_waitcnt vmcnt(8)
	s_waitcnt lgkmcnt(0)
	s_setprio 1
	s_barrier
	v_mfma_f32_16x16x32_bf16 v[124:127], v[128:131], v[160:163], v[124:127]
	v_mfma_f32_16x16x32_bf16 v[120:123], v[136:139], v[160:163], v[120:123]
	v_mfma_f32_16x16x32_bf16 v[112:115], v[128:131], v[184:187], v[112:115]
	v_mfma_f32_16x16x32_bf16 v[104:107], v[136:139], v[184:187], v[104:107]
	v_mfma_f32_16x16x32_bf16 v[96:99], v[128:131], v[200:203], v[96:99]
	v_mfma_f32_16x16x32_bf16 v[88:91], v[136:139], v[200:203], v[88:91]
	v_mfma_f32_16x16x32_bf16 v[80:83], v[128:131], v[208:211], v[80:83]
	v_mfma_f32_16x16x32_bf16 v[72:75], v[136:139], v[208:211], v[72:75]
	v_mfma_f32_16x16x32_bf16 v[124:127], v[132:135], v[180:183], v[124:127]
	v_mfma_f32_16x16x32_bf16 v[120:123], v[140:143], v[180:183], v[120:123]
	v_mfma_f32_16x16x32_bf16 v[112:115], v[132:135], v[188:191], v[112:115]
	v_mfma_f32_16x16x32_bf16 v[104:107], v[140:143], v[188:191], v[104:107]
	v_mfma_f32_16x16x32_bf16 v[96:99], v[132:135], v[204:207], v[96:99]
	v_mfma_f32_16x16x32_bf16 v[88:91], v[140:143], v[204:207], v[88:91]
	v_mfma_f32_16x16x32_bf16 v[80:83], v[132:135], v[212:215], v[80:83]
	v_mfma_f32_16x16x32_bf16 v[72:75], v[140:143], v[212:215], v[72:75]
	s_setprio 0
	s_setprio 1
	v_mfma_f32_16x16x32_bf16 v[116:119], v[144:147], v[160:163], v[116:119]
	v_mfma_f32_16x16x32_bf16 v[108:111], v[152:155], v[160:163], v[108:111]
	v_mfma_f32_16x16x32_bf16 v[100:103], v[144:147], v[184:187], v[100:103]
	v_mfma_f32_16x16x32_bf16 v[92:95], v[152:155], v[184:187], v[92:95]
	v_mfma_f32_16x16x32_bf16 v[84:87], v[144:147], v[200:203], v[84:87]
	v_mfma_f32_16x16x32_bf16 v[76:79], v[152:155], v[200:203], v[76:79]
	v_mfma_f32_16x16x32_bf16 v[68:71], v[144:147], v[208:211], v[68:71]
	v_mfma_f32_16x16x32_bf16 v[64:67], v[152:155], v[208:211], v[64:67]
	v_mfma_f32_16x16x32_bf16 v[116:119], v[148:151], v[180:183], v[116:119]
	v_mfma_f32_16x16x32_bf16 v[108:111], v[156:159], v[180:183], v[108:111]
	v_mfma_f32_16x16x32_bf16 v[100:103], v[148:151], v[188:191], v[100:103]
	v_mfma_f32_16x16x32_bf16 v[92:95], v[156:159], v[188:191], v[92:95]
	v_mfma_f32_16x16x32_bf16 v[84:87], v[148:151], v[204:207], v[84:87]
	v_mfma_f32_16x16x32_bf16 v[76:79], v[156:159], v[204:207], v[76:79]
	v_mfma_f32_16x16x32_bf16 v[68:71], v[148:151], v[212:215], v[68:71]
	v_mfma_f32_16x16x32_bf16 v[64:67], v[156:159], v[212:215], v[64:67]
	s_barrier
	s_setprio 0
	s_add_i32 s16, s47, s25
	v_lshl_add_u64 v[192:193], v[192:193], 0, s[10:11]
	s_mov_b32 m0, s16
	s_nop 0
	global_load_lds_dwordx4 v[192:193], off
	s_add_i32 m0, s16, 0x2000
	s_add_u32 s16, s20, 0xb0080
	v_lshl_add_u64 v[192:193], v[216:217], 0, s[10:11]
	s_addc_u32 s17, s21, 0
	s_add_i32 s20, s48, s25
	global_load_lds_dwordx4 v[192:193], off
	v_lshl_add_u64 v[192:193], s[16:17], 0, v[166:167]
	s_mov_b32 m0, s20
	s_nop 0
	global_load_lds_dwordx4 v[192:193], off
	v_lshl_add_u64 v[192:193], s[16:17], 0, v[170:171]
	s_add_i32 m0, s20, 0x2000
	s_nop 0
	global_load_lds_dwordx4 v[192:193], off
	v_lshl_add_u64 v[192:193], v[218:219], 0, s[10:11]
	s_mov_b32 m0, s35
	s_nop 0
	global_load_lds_dwordx4 v[192:193], off
	v_lshl_add_u64 v[192:193], v[220:221], 0, s[10:11]
	s_mov_b32 m0, s36
	s_nop 0
	global_load_lds_dwordx4 v[192:193], off
	ds_read_b128 v[160:163], v199 offset:49152
	ds_read_b128 v[180:183], v199 offset:50176
	ds_read_b128 v[184:187], v199 offset:51200
	ds_read_b128 v[188:191], v199 offset:52224
	ds_read_b128 v[200:203], v199 offset:53248
	ds_read_b128 v[204:207], v199 offset:54272
	ds_read_b128 v[208:211], v199 offset:55296
	ds_read_b128 v[212:215], v199 offset:56320
	s_waitcnt vmcnt(8)
	s_waitcnt lgkmcnt(0)
	s_setprio 1
	s_barrier
	v_mfma_f32_16x16x32_bf16 v[60:63], v[128:131], v[160:163], v[60:63]
	v_mfma_f32_16x16x32_bf16 v[56:59], v[136:139], v[160:163], v[56:59]
	v_mfma_f32_16x16x32_bf16 v[48:51], v[128:131], v[184:187], v[48:51]
	v_mfma_f32_16x16x32_bf16 v[40:43], v[136:139], v[184:187], v[40:43]
	v_mfma_f32_16x16x32_bf16 v[32:35], v[128:131], v[200:203], v[32:35]
	v_mfma_f32_16x16x32_bf16 v[24:27], v[136:139], v[200:203], v[24:27]
	v_mfma_f32_16x16x32_bf16 v[16:19], v[128:131], v[208:211], v[16:19]
	v_mfma_f32_16x16x32_bf16 v[8:11], v[136:139], v[208:211], v[8:11]
	v_mfma_f32_16x16x32_bf16 v[60:63], v[132:135], v[180:183], v[60:63]
	v_mfma_f32_16x16x32_bf16 v[56:59], v[140:143], v[180:183], v[56:59]
	v_mfma_f32_16x16x32_bf16 v[48:51], v[132:135], v[188:191], v[48:51]
	v_mfma_f32_16x16x32_bf16 v[40:43], v[140:143], v[188:191], v[40:43]
	v_mfma_f32_16x16x32_bf16 v[32:35], v[132:135], v[204:207], v[32:35]
	v_mfma_f32_16x16x32_bf16 v[24:27], v[140:143], v[204:207], v[24:27]
	v_mfma_f32_16x16x32_bf16 v[16:19], v[132:135], v[212:215], v[16:19]
	v_mfma_f32_16x16x32_bf16 v[8:11], v[140:143], v[212:215], v[8:11]
	s_setprio 0
	s_setprio 1
	v_mfma_f32_16x16x32_bf16 v[52:55], v[144:147], v[160:163], v[52:55]
	v_mfma_f32_16x16x32_bf16 v[44:47], v[152:155], v[160:163], v[44:47]
	v_mfma_f32_16x16x32_bf16 v[36:39], v[144:147], v[184:187], v[36:39]
	v_mfma_f32_16x16x32_bf16 v[28:31], v[152:155], v[184:187], v[28:31]
	v_mfma_f32_16x16x32_bf16 v[20:23], v[144:147], v[200:203], v[20:23]
	v_mfma_f32_16x16x32_bf16 v[12:15], v[152:155], v[200:203], v[12:15]
	v_mfma_f32_16x16x32_bf16 v[4:7], v[144:147], v[208:211], v[4:7]
	v_mfma_f32_16x16x32_bf16 v[0:3], v[152:155], v[208:211], v[0:3]
	v_mfma_f32_16x16x32_bf16 v[52:55], v[148:151], v[180:183], v[52:55]
	v_mfma_f32_16x16x32_bf16 v[44:47], v[156:159], v[180:183], v[44:47]
	v_mfma_f32_16x16x32_bf16 v[36:39], v[148:151], v[188:191], v[36:39]
	v_mfma_f32_16x16x32_bf16 v[28:31], v[156:159], v[188:191], v[28:31]
	v_mfma_f32_16x16x32_bf16 v[20:23], v[148:151], v[204:207], v[20:23]
	v_mfma_f32_16x16x32_bf16 v[12:15], v[156:159], v[204:207], v[12:15]
	v_mfma_f32_16x16x32_bf16 v[4:7], v[148:151], v[212:215], v[4:7]
	v_mfma_f32_16x16x32_bf16 v[0:3], v[156:159], v[212:215], v[0:3]
	s_barrier
	s_setprio 0
	s_add_i32 s46, s46, 2
	s_add_u32 s44, s44, 0x100
	s_addc_u32 s45, s45, 0
	s_cmp_gt_u32 s46, 41
	s_mov_b64 s[16:17], s[18:19]
	s_cbranch_scc0 .LBB0_1273
	s_and_b64 vcc, exec, s[12:13]
	s_cbranch_vccz .LBB0_1276
	s_barrier
	s_setprio 1
